# up-GEMM epilogue: wave-uniform fast path without the 170 sequence-boundary zero-padding selects (original code kept as slow path)
# speedup vs baseline: 1.0068x; 1.0068x over previous
;     __device__ __forceinline__ void operator()(const f32x4 (&acc)[2][2][4][2], const Unit& u, int wr, int wc, int fr, int fq) const {
;         const int grow0 = 252 * u.pm + 126 * wr - 1 + 8 * fr;
;         const int cg0 = 128 * u.pn + 32 * wc + 8 * fq;
;         float rs[8]; bool pz[8], nz[8];
; #pragma unroll
;         for (int i = 0; i < 8; ++i) { const int t = T0 + grow0 + i; const int tc = t < 0 ? 0 : (t > MTOK - 1 ? MTOK - 1 : t); rs[i] = rstd[tc];
;             pz[i] = ((t & 8191) == 0) && (t != 24576); nz[i] = (((t + 1) & 8191) == 0) && (t + 1 != 24576); }
; #pragma unroll
;         for (int n = 0; n < 2; ++n) {
;             float res[8][4];
; #pragma unroll
;             for (int j = 0; j < 4; ++j) {
;                 const int cg = cg0 + 4 * n + j;
;                 const float gw0 = cw[cg], gw1 = cw[NUP + cg], gw2 = cw[2 * NUP + cg], gb = cb[cg];
;                 const float vw0 = cw[DFF + cg], vw1 = cw[NUP + DFF + cg], vw2 = cw[2 * NUP + DFF + cg], vb = cb[DFF + cg];
;                 float xg[8], xv[8];
; #pragma unroll
;                 for (int i = 0; i < 8; ++i) { xg[i] = acc[i >> 2][0][i & 3][n][j] * rs[i]; xv[i] = acc[i >> 2][1][i & 3][n][j] * rs[i]; }
;                 const float gp = __builtin_bit_cast(float, __builtin_amdgcn_update_dpp(0, __builtin_bit_cast(int, xg[7]), 0x111, 0xf, 0xf, false));
;                 const float gn = __builtin_bit_cast(float, __builtin_amdgcn_update_dpp(0, __builtin_bit_cast(int, xg[0]), 0x101, 0xf, 0xf, false));
;                 const float vp = __builtin_bit_cast(float, __builtin_amdgcn_update_dpp(0, __builtin_bit_cast(int, xv[7]), 0x111, 0xf, 0xf, false));
;                 const float vn = __builtin_bit_cast(float, __builtin_amdgcn_update_dpp(0, __builtin_bit_cast(int, xv[0]), 0x101, 0xf, 0xf, false));
.LBB0_598:
	s_mul_i32 s10, s22, 0xfc
	v_add_u32_e32 v189, s10, v252
	v_add_u32_e32 v106, s48, v189
	v_add_u32_e32 v107, 8, v106
	v_and_b32_e32 v107, 0x1fff, v107
	v_cmp_gt_u32_e32 vcc, 9, v107
	s_cbranch_vccz .Lupf_start
	v_add_u32_e32 v195, 7, v106
	v_med3_i32 v107, v106, 0, s65
	v_add_u32_e32 v203, 1, v106
	v_add_u32_e32 v191, 2, v106
	v_add_u32_e32 v193, 3, v106
	v_add_u32_e32 v201, 4, v106
	v_add_u32_e32 v199, 5, v106
	v_add_u32_e32 v197, 6, v106
	v_med3_i32 v106, v195, 0, s65
	v_lshl_or_b32 v186, s12, 7, v253
	v_lshlrev_b32_e32 v107, 2, v107
	v_med3_i32 v108, v203, 0, s65
	v_lshlrev_b32_e32 v106, 2, v106
	v_ashrrev_i32_e32 v187, 31, v186
	v_lshlrev_b32_e32 v108, 2, v108
	global_load_dword v198, v107, s[42:43]
	global_load_dword v200, v108, s[42:43]
	global_load_dword v202, v106, s[42:43]
	v_lshlrev_b64 v[106:107], 2, v[186:187]
	v_lshl_add_u64 v[206:207], s[52:53], 0, v[106:107]
	s_movk_i32 s10, 0x5000
	v_add_co_u32_e32 v208, vcc, s10, v206
	v_med3_i32 v109, v191, 0, s65
	s_nop 0
	v_addc_co_u32_e32 v209, vcc, 0, v207, vcc
	v_add_co_u32_e32 v210, vcc, s84, v206
	s_mov_b32 s10, 0xd000
	s_nop 0
	v_addc_co_u32_e32 v211, vcc, 0, v207, vcc
	v_add_co_u32_e32 v212, vcc, s66, v206
	v_lshlrev_b32_e32 v188, 2, v109
	s_nop 0
	v_addc_co_u32_e32 v213, vcc, 0, v207, vcc
	v_add_co_u32_e32 v214, vcc, s45, v206
	v_med3_i32 v109, v193, 0, s65
	s_nop 0
	v_addc_co_u32_e32 v215, vcc, 0, v207, vcc
	v_add_co_u32_e32 v216, vcc, s10, v206
	v_lshlrev_b32_e32 v190, 2, v109
	v_med3_i32 v109, v201, 0, s65
	v_lshl_add_u64 v[204:205], s[54:55], 0, v[106:107]
	v_addc_co_u32_e32 v217, vcc, 0, v207, vcc
	v_lshlrev_b32_e32 v192, 2, v109
	v_med3_i32 v109, v199, 0, s65
	v_add_co_u32_e32 v218, vcc, s66, v204
	v_lshlrev_b32_e32 v220, 2, v109
	v_med3_i32 v109, v197, 0, s65
	v_addc_co_u32_e32 v219, vcc, 0, v205, vcc
	v_lshlrev_b32_e32 v221, 2, v109
	global_load_dwordx4 v[106:109], v[206:207], off
	global_load_dwordx4 v[122:125], v[208:209], off offset:2048
	global_load_dwordx4 v[110:113], v[210:211], off
	global_load_dwordx4 v[118:121], v[204:205], off
	global_load_dwordx4 v[114:117], v[212:213], off offset:3072
	global_load_dwordx4 v[126:129], v[214:215], off offset:1024
	global_load_dwordx4 v[130:133], v[216:217], off offset:3072
	global_load_dwordx4 v[138:141], v[218:219], off offset:3072
	global_load_dword v196, v188, s[42:43]
	global_load_dword v194, v190, s[42:43]
	s_nop 0
	global_load_dword v192, v192, s[42:43]
	s_nop 0
	global_load_dword v190, v220, s[42:43]
	global_load_dword v188, v221, s[42:43]
	v_and_b32_e32 v220, 0x1fff, v203
	v_cmp_ne_u32_e32 vcc, s67, v203
	v_cmp_eq_u32_e64 s[10:11], 0, v220
	v_mov_b32_e32 v234, 0
	v_mov_b32_e32 v232, 0
	v_mov_b32_e32 v235, 0
	v_mov_b32_e32 v233, 0
	s_and_b64 s[94:95], vcc, s[10:11]
	v_mov_b32_e32 v238, 0
	v_mov_b32_e32 v236, 0
	v_mov_b32_e32 v239, 0
	v_mov_b32_e32 v237, 0
	v_cmp_gt_i32_e32 vcc, s47, v189
	s_and_b64 s[88:89], s[4:5], vcc
	s_waitcnt vmcnt(0)
	v_pk_mul_f32 v[228:229], v[158:159], v[198:199] op_sel_hi:[1,0]
	v_pk_mul_f32 v[222:223], v[154:155], v[200:201] op_sel_hi:[1,0]
	v_pk_mul_f32 v[158:159], v[142:143], v[202:203] op_sel_hi:[1,0]
	v_pk_mul_f32 v[142:143], v[134:135], v[202:203] op_sel_hi:[1,0]
	v_pk_mul_f32 v[220:221], v[146:147], v[200:201] op_sel_hi:[1,0]
	v_mov_b32_e32 v154, 0
	v_pk_mul_f32 v[230:231], v[150:151], v[198:199] op_sel_hi:[1,0]
	v_mov_b32_e32 v146, 0
	v_mov_b32_e32 v155, 0
	v_mov_b32_e32 v147, 0
	v_pk_mul_f32 v[144:145], v[144:145], v[202:203] op_sel_hi:[1,0]
	v_pk_mul_f32 v[134:135], v[136:137], v[202:203] op_sel_hi:[1,0]
	v_pk_mul_f32 v[150:151], v[148:149], v[200:201] op_sel_hi:[1,0]
	v_pk_mul_f32 v[224:225], v[160:161], v[198:199] op_sel_hi:[1,0]
	v_mov_b32_e32 v148, 0
	v_pk_mul_f32 v[226:227], v[152:153], v[198:199] op_sel_hi:[1,0]
	v_mov_b32_e32 v136, 0
	v_mov_b32_e32 v149, 0
	v_mov_b32_e32 v137, 0
	v_mov_b32_dpp v234, v158 row_shr:1 row_mask:0xf bank_mask:0xf
	v_mov_b32_dpp v232, v142 row_shr:1 row_mask:0xf bank_mask:0xf
	v_mov_b32_dpp v235, v159 row_shr:1 row_mask:0xf bank_mask:0xf
	v_mov_b32_dpp v233, v143 row_shr:1 row_mask:0xf bank_mask:0xf
	v_mov_b32_dpp v154, v228 row_shl:1 row_mask:0xf bank_mask:0xf
	v_mov_b32_dpp v146, v230 row_shl:1 row_mask:0xf bank_mask:0xf
	v_mov_b32_dpp v155, v229 row_shl:1 row_mask:0xf bank_mask:0xf
	v_mov_b32_dpp v147, v231 row_shl:1 row_mask:0xf bank_mask:0xf
	v_mov_b32_dpp v238, v144 row_shr:1 row_mask:0xf bank_mask:0xf
	v_mov_b32_dpp v236, v134 row_shr:1 row_mask:0xf bank_mask:0xf
	v_mov_b32_dpp v239, v145 row_shr:1 row_mask:0xf bank_mask:0xf
	v_mov_b32_dpp v237, v135 row_shr:1 row_mask:0xf bank_mask:0xf
	v_pk_mul_f32 v[156:157], v[156:157], v[200:201] op_sel_hi:[1,0]
	v_mov_b32_dpp v148, v224 row_shl:1 row_mask:0xf bank_mask:0xf
	v_mov_b32_dpp v136, v226 row_shl:1 row_mask:0xf bank_mask:0xf
	v_mov_b32_dpp v149, v225 row_shl:1 row_mask:0xf bank_mask:0xf
	v_mov_b32_dpp v137, v227 row_shl:1 row_mask:0xf bank_mask:0xf
	s_and_saveexec_b64 s[10:11], s[88:89]
	s_cbranch_execz .LBB0_600
;     __device__ __forceinline__ void operator()(const f32x4 (&acc)[2][2][4][2], const Unit& u, int wr, int wc, int fr, int fq) const {
;     ...
;                 for (int i = 0; i < 8; ++i) {
;                     float pg = i > 0 ? xg[i - 1] : gp, ng = i < 7 ? xg[i + 1] : gn, pv = i > 0 ? xv[i - 1] : vp, nv = i < 7 ? xv[i + 1] : vn;
;                     if (pz[i]) { pg = 0.f; pv = 0.f; } if (nz[i]) { ng = 0.f; nv = 0.f; }
;                     const float cgv = gw0 * pg + gw1 * xg[i] + gw2 * ng + gb;
;                     const float cvv = vw0 * pv + vw1 * xv[i] + vw2 * nv + vb;
;                     res[i][j] = gelu_tanh(cgv) * cvv;
;                 }
;             }
; #pragma unroll
;             for (int i = 0; i < 8; ++i) { const int s = 8 * fr + i, grow = grow0 + i;
;                 if (s >= 1 && s <= 126 && grow < HALF_TOK) { u32x2 w; w.x = pk2(res[i][0], res[i][1]); w.y = pk2(res[i][2], res[i][3]); *(u32x2*)(G + (size_t)grow * DFF + cg0 + 4 * n) = w; } }
	v_pk_mul_f32 v[152:153], v[108:109], v[238:239]
	v_cndmask_b32_e64 v161, v157, 0, s[94:95]
	v_pk_fma_f32 v[152:153], v[224:225], v[124:125], v[152:153]
	v_cndmask_b32_e64 v160, v156, 0, s[94:95]
	v_pk_fma_f32 v[152:153], v[160:161], v[112:113], v[152:153]
	v_pk_mul_f32 v[236:237], v[116:117], v[236:237]
	v_pk_add_f32 v[152:153], v[120:121], v[152:153]
	v_pk_fma_f32 v[236:237], v[226:227], v[128:129], v[236:237]
	v_pk_mul_f32 v[160:161], v[152:153], v[152:153]
	v_cndmask_b32_e64 v239, v151, 0, s[94:95]
	v_fmamk_f32 v161, v161, 0xbdd2d3e8, v245
	v_fmamk_f32 v160, v160, 0xbdd2d3e8, v245
	v_cndmask_b32_e64 v238, v150, 0, s[94:95]
	v_pk_mul_f32 v[234:235], v[106:107], v[234:235]
	v_mul_f32_e32 v161, v153, v161
	v_mul_f32_e32 v160, v152, v160
	v_pk_fma_f32 v[236:237], v[238:239], v[132:133], v[236:237]
	v_pk_fma_f32 v[234:235], v[228:229], v[122:123], v[234:235]
	v_cndmask_b32_e64 v239, v223, 0, s[94:95]
	v_cndmask_b32_e64 v238, v222, 0, s[94:95]
	v_exp_f32_e32 v161, v161
	v_exp_f32_e32 v160, v160
	v_pk_fma_f32 v[234:235], v[238:239], v[110:111], v[234:235]
	v_pk_add_f32 v[236:237], v[140:141], v[236:237]
	v_pk_add_f32 v[234:235], v[118:119], v[234:235]
	v_add_f32_e32 v161, 1.0, v161
	v_pk_mul_f32 v[238:239], v[234:235], v[234:235]
	v_add_f32_e32 v160, 1.0, v160
	v_fmamk_f32 v203, v239, 0xbdd2d3e8, v245
	v_mul_f32_e32 v203, v235, v203
	v_rcp_f32_e32 v161, v161
	v_rcp_f32_e32 v160, v160
	v_exp_f32_e32 v203, v203
	v_pk_mul_f32 v[232:233], v[114:115], v[232:233]
	v_pk_mul_f32 v[152:153], v[152:153], v[160:161]
	v_add_f32_e32 v160, 1.0, v203
	v_rcp_f32_e32 v161, v160
	v_fmamk_f32 v160, v238, 0xbdd2d3e8, v245
	v_mul_f32_e32 v160, v234, v160
	v_exp_f32_e32 v160, v160
	v_pk_mul_f32 v[152:153], v[236:237], v[152:153]
	v_pk_fma_f32 v[232:233], v[230:231], v[126:127], v[232:233]
	v_cndmask_b32_e64 v237, v221, 0, s[94:95]
	v_add_f32_e32 v160, 1.0, v160
	v_rcp_f32_e32 v160, v160
	v_cndmask_b32_e64 v236, v220, 0, s[94:95]
	v_pk_fma_f32 v[232:233], v[236:237], v[130:131], v[232:233]
	v_pk_mul_f32 v[160:161], v[234:235], v[160:161]
	v_pk_add_f32 v[232:233], v[138:139], v[232:233]
	s_nop 0
	v_pk_mul_f32 v[160:161], v[232:233], v[160:161]
	s_nop 0
	v_cvt_pk_bf16_f32 v160, v160, v161
	v_cvt_pk_bf16_f32 v161, v152, v153
	v_mov_b64_e32 v[152:153], s[34:35]
	v_mad_i64_i32 v[152:153], s[12:13], v189, s85, v[152:153]
	v_lshl_add_u64 v[152:153], v[186:187], 1, v[152:153]
	global_store_dwordx2 v[152:153], v[160:161], off

;     __device__ __forceinline__ void operator()(const f32x4 (&acc)[2][2][4][2], const Unit& u, int wr, int wc, int fr, int fq) const {
;         const int grow0 = 252 * u.pm + 126 * wr - 1 + 8 * fr;
;         const int cg0 = 128 * u.pn + 32 * wc + 8 * fq;
;         float rs[8]; bool pz[8], nz[8];
; #pragma unroll
;         for (int i = 0; i < 8; ++i) { const int t = T0 + grow0 + i; const int tc = t < 0 ? 0 : (t > MTOK - 1 ? MTOK - 1 : t); rs[i] = rstd[tc];
;             pz[i] = ((t & 8191) == 0) && (t != 24576); nz[i] = (((t + 1) & 8191) == 0) && (t + 1 != 24576); }
; #pragma unroll
;         for (int n = 0; n < 2; ++n) {
;             float res[8][4];
; #pragma unroll
;             for (int j = 0; j < 4; ++j) {
;                 const int cg = cg0 + 4 * n + j;
;                 const float gw0 = cw[cg], gw1 = cw[NUP + cg], gw2 = cw[2 * NUP + cg], gb = cb[cg];
;                 const float vw0 = cw[DFF + cg], vw1 = cw[NUP + DFF + cg], vw2 = cw[2 * NUP + DFF + cg], vb = cb[DFF + cg];
;                 float xg[8], xv[8];
; #pragma unroll
;                 for (int i = 0; i < 8; ++i) { xg[i] = acc[i >> 2][0][i & 3][n][j] * rs[i]; xv[i] = acc[i >> 2][1][i & 3][n][j] * rs[i]; }
;                 const float gp = __builtin_bit_cast(float, __builtin_amdgcn_update_dpp(0, __builtin_bit_cast(int, xg[7]), 0x111, 0xf, 0xf, false));
;                 const float gn = __builtin_bit_cast(float, __builtin_amdgcn_update_dpp(0, __builtin_bit_cast(int, xg[0]), 0x101, 0xf, 0xf, false));
;                 const float vp = __builtin_bit_cast(float, __builtin_amdgcn_update_dpp(0, __builtin_bit_cast(int, xv[7]), 0x111, 0xf, 0xf, false));
;                 const float vn = __builtin_bit_cast(float, __builtin_amdgcn_update_dpp(0, __builtin_bit_cast(int, xv[0]), 0x101, 0xf, 0xf, false));
; #pragma unroll
;                 for (int i = 0; i < 8; ++i) {
;                     float pg = i > 0 ? xg[i - 1] : gp, ng = i < 7 ? xg[i + 1] : gn, pv = i > 0 ? xv[i - 1] : vp, nv = i < 7 ? xv[i + 1] : vn;
;                     if (pz[i]) { pg = 0.f; pv = 0.f; } if (nz[i]) { ng = 0.f; nv = 0.f; }
;                     const float cgv = gw0 * pg + gw1 * xg[i] + gw2 * ng + gb;
;                     const float cvv = vw0 * pv + vw1 * xv[i] + vw2 * nv + vb;
;                     res[i][j] = gelu_tanh(cgv) * cvv;
;                 }
;             }
; #pragma unroll
.Lupf_start:
	v_add_u32_e32 v195, 7, v106
	v_med3_i32 v107, v106, 0, s65
	v_add_u32_e32 v203, 1, v106
	v_add_u32_e32 v191, 2, v106
	v_add_u32_e32 v193, 3, v106
	v_add_u32_e32 v201, 4, v106
	v_add_u32_e32 v199, 5, v106
	v_add_u32_e32 v197, 6, v106
	v_med3_i32 v106, v195, 0, s65
	v_lshl_or_b32 v186, s12, 7, v253
	v_lshlrev_b32_e32 v107, 2, v107
	v_med3_i32 v108, v203, 0, s65
	v_lshlrev_b32_e32 v106, 2, v106
	v_ashrrev_i32_e32 v187, 31, v186
	v_lshlrev_b32_e32 v108, 2, v108
	global_load_dword v198, v107, s[42:43]
	global_load_dword v200, v108, s[42:43]
	global_load_dword v202, v106, s[42:43]
	v_lshlrev_b64 v[106:107], 2, v[186:187]
	v_lshl_add_u64 v[206:207], s[52:53], 0, v[106:107]
	s_movk_i32 s10, 0x5000
	v_add_co_u32_e32 v208, vcc, s10, v206
	v_med3_i32 v109, v191, 0, s65
	s_nop 0
	v_addc_co_u32_e32 v209, vcc, 0, v207, vcc
	v_add_co_u32_e32 v210, vcc, s84, v206
	s_mov_b32 s10, 0xd000
	s_nop 0
	v_addc_co_u32_e32 v211, vcc, 0, v207, vcc
	v_add_co_u32_e32 v212, vcc, s66, v206
	v_lshlrev_b32_e32 v188, 2, v109
	s_nop 0
	v_addc_co_u32_e32 v213, vcc, 0, v207, vcc
	v_add_co_u32_e32 v214, vcc, s45, v206
	v_med3_i32 v109, v193, 0, s65
	s_nop 0
	v_addc_co_u32_e32 v215, vcc, 0, v207, vcc
	v_add_co_u32_e32 v216, vcc, s10, v206
	v_lshlrev_b32_e32 v190, 2, v109
	v_med3_i32 v109, v201, 0, s65
	v_lshl_add_u64 v[204:205], s[54:55], 0, v[106:107]
	v_addc_co_u32_e32 v217, vcc, 0, v207, vcc
	v_lshlrev_b32_e32 v192, 2, v109
	v_med3_i32 v109, v199, 0, s65
	v_add_co_u32_e32 v218, vcc, s66, v204
	v_lshlrev_b32_e32 v220, 2, v109
	v_med3_i32 v109, v197, 0, s65
	v_addc_co_u32_e32 v219, vcc, 0, v205, vcc
	v_lshlrev_b32_e32 v221, 2, v109
	global_load_dwordx4 v[106:109], v[206:207], off
	global_load_dwordx4 v[122:125], v[208:209], off offset:2048
	global_load_dwordx4 v[110:113], v[210:211], off
	global_load_dwordx4 v[118:121], v[204:205], off
	global_load_dwordx4 v[114:117], v[212:213], off offset:3072
	global_load_dwordx4 v[126:129], v[214:215], off offset:1024
	global_load_dwordx4 v[130:133], v[216:217], off offset:3072
	global_load_dwordx4 v[138:141], v[218:219], off offset:3072
	global_load_dword v196, v188, s[42:43]
	global_load_dword v194, v190, s[42:43]
	s_nop 0
	global_load_dword v192, v192, s[42:43]
	s_nop 0
	global_load_dword v190, v220, s[42:43]
	global_load_dword v188, v221, s[42:43]
	v_and_b32_e32 v220, 0x1fff, v203
	v_cmp_ne_u32_e32 vcc, s67, v203
	v_cmp_eq_u32_e64 s[10:11], 0, v220
	v_mov_b32_e32 v234, 0
	v_mov_b32_e32 v232, 0
	v_mov_b32_e32 v235, 0
	v_mov_b32_e32 v233, 0
	s_and_b64 s[94:95], vcc, s[10:11]
	v_mov_b32_e32 v238, 0
	v_mov_b32_e32 v236, 0
	v_mov_b32_e32 v239, 0
	v_mov_b32_e32 v237, 0
	v_cmp_gt_i32_e32 vcc, s47, v189
	s_and_b64 s[88:89], s[4:5], vcc
	s_waitcnt vmcnt(0)
	v_pk_mul_f32 v[228:229], v[158:159], v[198:199] op_sel_hi:[1, 0]
	v_pk_mul_f32 v[222:223], v[154:155], v[200:201] op_sel_hi:[1, 0]
	v_pk_mul_f32 v[158:159], v[142:143], v[202:203] op_sel_hi:[1, 0]
	v_pk_mul_f32 v[142:143], v[134:135], v[202:203] op_sel_hi:[1, 0]
	v_pk_mul_f32 v[220:221], v[146:147], v[200:201] op_sel_hi:[1, 0]
	v_mov_b32_e32 v154, 0
	v_pk_mul_f32 v[230:231], v[150:151], v[198:199] op_sel_hi:[1, 0]
	v_mov_b32_e32 v146, 0
	v_mov_b32_e32 v155, 0
	v_mov_b32_e32 v147, 0
	v_pk_mul_f32 v[144:145], v[144:145], v[202:203] op_sel_hi:[1, 0]
	v_pk_mul_f32 v[134:135], v[136:137], v[202:203] op_sel_hi:[1, 0]
	v_pk_mul_f32 v[150:151], v[148:149], v[200:201] op_sel_hi:[1, 0]
	v_pk_mul_f32 v[224:225], v[160:161], v[198:199] op_sel_hi:[1, 0]
	v_mov_b32_e32 v148, 0
	v_pk_mul_f32 v[226:227], v[152:153], v[198:199] op_sel_hi:[1, 0]
	v_mov_b32_e32 v136, 0
	v_mov_b32_e32 v149, 0
	v_mov_b32_e32 v137, 0
	v_mov_b32_dpp v234, v158 row_shr:1 row_mask:0xf bank_mask:0xf
	v_mov_b32_dpp v232, v142 row_shr:1 row_mask:0xf bank_mask:0xf
	v_mov_b32_dpp v235, v159 row_shr:1 row_mask:0xf bank_mask:0xf
	v_mov_b32_dpp v233, v143 row_shr:1 row_mask:0xf bank_mask:0xf
	v_mov_b32_dpp v154, v228 row_shl:1 row_mask:0xf bank_mask:0xf
	v_mov_b32_dpp v146, v230 row_shl:1 row_mask:0xf bank_mask:0xf
	v_mov_b32_dpp v155, v229 row_shl:1 row_mask:0xf bank_mask:0xf
	v_mov_b32_dpp v147, v231 row_shl:1 row_mask:0xf bank_mask:0xf
	v_mov_b32_dpp v238, v144 row_shr:1 row_mask:0xf bank_mask:0xf
	v_mov_b32_dpp v236, v134 row_shr:1 row_mask:0xf bank_mask:0xf
	v_mov_b32_dpp v239, v145 row_shr:1 row_mask:0xf bank_mask:0xf
	v_mov_b32_dpp v237, v135 row_shr:1 row_mask:0xf bank_mask:0xf
	v_pk_mul_f32 v[156:157], v[156:157], v[200:201] op_sel_hi:[1, 0]
	v_mov_b32_dpp v148, v224 row_shl:1 row_mask:0xf bank_mask:0xf
	v_mov_b32_dpp v136, v226 row_shl:1 row_mask:0xf bank_mask:0xf
	v_mov_b32_dpp v149, v225 row_shl:1 row_mask:0xf bank_mask:0xf
	v_mov_b32_dpp v137, v227 row_shl:1 row_mask:0xf bank_mask:0xf
	s_and_saveexec_b64 s[10:11], s[88:89]
	s_cbranch_execz .Lupf_600
	v_pk_mul_f32 v[152:153], v[108:109], v[238:239]
	v_pk_fma_f32 v[152:153], v[224:225], v[124:125], v[152:153]
	v_pk_fma_f32 v[152:153], v[156:157], v[112:113], v[152:153]
	v_pk_mul_f32 v[236:237], v[116:117], v[236:237]
	v_pk_add_f32 v[152:153], v[120:121], v[152:153]
	v_pk_fma_f32 v[236:237], v[226:227], v[128:129], v[236:237]
	v_pk_mul_f32 v[160:161], v[152:153], v[152:153]
	v_fmamk_f32 v161, v161, 0xbdd2d3e8, v245
	v_fmamk_f32 v160, v160, 0xbdd2d3e8, v245
	v_pk_mul_f32 v[234:235], v[106:107], v[234:235]
	v_mul_f32_e32 v161, v153, v161
	v_mul_f32_e32 v160, v152, v160
	v_pk_fma_f32 v[236:237], v[150:151], v[132:133], v[236:237]
	v_pk_fma_f32 v[234:235], v[228:229], v[122:123], v[234:235]
	v_exp_f32_e32 v161, v161
	v_exp_f32_e32 v160, v160
	v_pk_fma_f32 v[234:235], v[222:223], v[110:111], v[234:235]
	v_pk_add_f32 v[236:237], v[140:141], v[236:237]
	v_pk_add_f32 v[234:235], v[118:119], v[234:235]
	v_add_f32_e32 v161, 1.0, v161
	v_pk_mul_f32 v[238:239], v[234:235], v[234:235]
	v_add_f32_e32 v160, 1.0, v160
	v_fmamk_f32 v203, v239, 0xbdd2d3e8, v245
	v_mul_f32_e32 v203, v235, v203
	v_rcp_f32_e32 v161, v161
	v_rcp_f32_e32 v160, v160
	v_exp_f32_e32 v203, v203
	v_pk_mul_f32 v[232:233], v[114:115], v[232:233]
	v_pk_mul_f32 v[152:153], v[152:153], v[160:161]
	v_add_f32_e32 v160, 1.0, v203
	v_rcp_f32_e32 v161, v160
	v_fmamk_f32 v160, v238, 0xbdd2d3e8, v245
	v_mul_f32_e32 v160, v234, v160
	v_exp_f32_e32 v160, v160
	v_pk_mul_f32 v[152:153], v[236:237], v[152:153]
	v_pk_fma_f32 v[232:233], v[230:231], v[126:127], v[232:233]
	v_add_f32_e32 v160, 1.0, v160
	v_rcp_f32_e32 v160, v160
	v_pk_fma_f32 v[232:233], v[220:221], v[130:131], v[232:233]
	v_pk_mul_f32 v[160:161], v[234:235], v[160:161]
	v_pk_add_f32 v[232:233], v[138:139], v[232:233]
	s_nop 0
	v_pk_mul_f32 v[160:161], v[232:233], v[160:161]
	s_nop 0
	v_cvt_pk_bf16_f32 v160, v160, v161
	v_cvt_pk_bf16_f32 v161, v152, v153
	v_mov_b64_e32 v[152:153], s[34:35]
	v_mad_i64_i32 v[152:153], s[12:13], v189, s85, v[152:153]
	v_lshl_add_u64 v[152:153], v[186:187], 1, v[152:153]
	global_store_dwordx2 v[152:153], v[160:161], off
;     __device__ __forceinline__ void operator()(const f32x4 (&acc)[2][2][4][2], const Unit& u, int wr, int wc, int fr, int fq) const {
;     ...
;                 for (int i = 0; i < 8; ++i) {
;                     float pg = i > 0 ? xg[i - 1] : gp, ng = i < 7 ? xg[i + 1] : gn, pv = i > 0 ? xv[i - 1] : vp, nv = i < 7 ? xv[i + 1] : vn;
;                     if (pz[i]) { pg = 0.f; pv = 0.f; } if (nz[i]) { ng = 0.f; nv = 0.f; }
;                     const float cgv = gw0 * pg + gw1 * xg[i] + gw2 * ng + gb;
;                     const float cvv = vw0 * pv + vw1 * xv[i] + vw2 * nv + vb;
;                     res[i][j] = gelu_tanh(cgv) * cvv;
;                 }
;             }
; #pragma unroll
;             for (int i = 0; i < 8; ++i) { const int s = 8 * fr + i, grow = grow0 + i;
;                 if (s >= 1 && s <= 126 && grow < HALF_TOK) { u32x2 w; w.x = pk2(res[i][0], res[i][1]); w.y = pk2(res[i][2], res[i][3]); *(u32x2*)(G + (size_t)grow * DFF + cg0 + 4 * n) = w; } }
.Lupf_600:
	s_or_b64 exec, exec, s[10:11]
	v_and_b32_e32 v152, 0x1fff, v191
	s_movk_i32 s10, 0x3fff
	v_cmp_eq_u32_e32 vcc, 0, v152
	v_pk_mul_f32 v[160:161], v[102:103], v[196:197] op_sel_hi:[1, 0]
	v_pk_mul_f32 v[152:153], v[98:99], v[196:197] op_sel_hi:[1, 0]
	v_pk_mul_f32 v[102:103], v[104:105], v[196:197] op_sel_hi:[1, 0]
	v_pk_mul_f32 v[98:99], v[100:101], v[196:197] op_sel_hi:[1, 0]
	v_add_u32_e32 v191, 1, v189
	v_cmp_gt_i32_e64 s[14:15], s10, v189
	s_and_saveexec_b64 s[10:11], s[14:15]
	s_cbranch_execz .Lupf_602
	v_mov_b32_e32 v101, v229
	v_mov_b32_e32 v100, v228
	v_pk_mul_f32 v[232:233], v[222:223], v[122:123]
	v_cndmask_b32_e64 v229, v161, 0, vcc
	v_cndmask_b32_e64 v228, v160, 0, vcc
	v_pk_fma_f32 v[100:101], v[100:101], v[106:107], v[232:233]
	v_mov_b32_e32 v105, v231
	v_pk_fma_f32 v[100:101], v[228:229], v[110:111], v[100:101]
	v_mov_b32_e32 v104, v230
	v_pk_add_f32 v[100:101], v[118:119], v[100:101]
	v_cndmask_b32_e64 v231, v153, 0, vcc
	v_pk_mul_f32 v[228:229], v[100:101], v[100:101]
	v_cndmask_b32_e64 v230, v152, 0, vcc
	v_fmamk_f32 v203, v228, 0xbdd2d3e8, v245
	v_mul_f32_e32 v203, v100, v203
	v_fmamk_f32 v228, v229, 0xbdd2d3e8, v245
	v_exp_f32_e32 v203, v203
	v_mul_f32_e32 v228, v101, v228
	v_exp_f32_e32 v233, v228
	v_pk_mul_f32 v[228:229], v[220:221], v[126:127]
	v_add_f32_e32 v203, 1.0, v203
	v_rcp_f32_e32 v232, v203
	v_add_f32_e32 v203, 1.0, v233
	v_rcp_f32_e32 v233, v203
	v_pk_fma_f32 v[104:105], v[104:105], v[114:115], v[228:229]
	v_cndmask_b32_e64 v229, v99, 0, vcc
	v_pk_fma_f32 v[104:105], v[230:231], v[130:131], v[104:105]
	v_pk_mul_f32 v[100:101], v[100:101], v[232:233]
	v_pk_add_f32 v[104:105], v[138:139], v[104:105]
	v_pk_mul_f32 v[230:231], v[156:157], v[124:125]
	v_pk_mul_f32 v[100:101], v[104:105], v[100:101]
	v_mov_b32_e32 v105, v225
	v_mov_b32_e32 v104, v224
	v_mov_b32_e32 v225, v227
	v_mov_b32_e32 v224, v226
	v_cndmask_b32_e64 v227, v103, 0, vcc
	v_cndmask_b32_e64 v226, v102, 0, vcc
	v_pk_fma_f32 v[104:105], v[104:105], v[108:109], v[230:231]
	v_cndmask_b32_e64 v228, v98, 0, vcc
	v_pk_fma_f32 v[104:105], v[226:227], v[112:113], v[104:105]
	v_cvt_pk_bf16_f32 v100, v100, v101
	v_pk_add_f32 v[104:105], v[120:121], v[104:105]
	s_nop 0
	v_pk_mul_f32 v[226:227], v[104:105], v[104:105]
	s_nop 0
	v_fmamk_f32 v203, v226, 0xbdd2d3e8, v245
	v_mul_f32_e32 v203, v104, v203
	v_fmamk_f32 v226, v227, 0xbdd2d3e8, v245
	v_exp_f32_e32 v203, v203
	v_mul_f32_e32 v226, v105, v226
	v_exp_f32_e32 v231, v226
	v_pk_mul_f32 v[226:227], v[150:151], v[128:129]
	v_add_f32_e32 v203, 1.0, v203
	v_rcp_f32_e32 v230, v203
	v_add_f32_e32 v203, 1.0, v231
	v_rcp_f32_e32 v231, v203
	v_pk_fma_f32 v[224:225], v[224:225], v[116:117], v[226:227]
	v_pk_mul_f32 v[104:105], v[104:105], v[230:231]
	v_pk_fma_f32 v[224:225], v[228:229], v[132:133], v[224:225]
	s_nop 0
	v_pk_add_f32 v[224:225], v[140:141], v[224:225]
	s_nop 0
	v_pk_mul_f32 v[104:105], v[224:225], v[104:105]
	s_nop 0
	v_cvt_pk_bf16_f32 v101, v104, v105
	v_mov_b64_e32 v[104:105], s[34:35]
	v_mad_i64_i32 v[104:105], s[12:13], v191, s85, v[104:105]
	v_lshl_add_u64 v[104:105], v[186:187], 1, v[104:105]
	global_store_dwordx2 v[104:105], v[100:101], off
.Lupf_602:
	s_or_b64 exec, exec, s[10:11]
	v_and_b32_e32 v100, 0x1fff, v193
	v_cmp_eq_u32_e64 s[10:11], 0, v100
	v_cmp_ne_u32_e64 s[12:13], s67, v193
	s_and_b64 s[96:97], s[12:13], s[10:11]
	s_movk_i32 s10, 0x3ffe
	v_pk_mul_f32 v[104:105], v[94:95], v[194:195] op_sel_hi:[1, 0]
	v_pk_mul_f32 v[100:101], v[90:91], v[194:195] op_sel_hi:[1, 0]
	v_pk_mul_f32 v[94:95], v[96:97], v[194:195] op_sel_hi:[1, 0]
	v_pk_mul_f32 v[90:91], v[92:93], v[194:195] op_sel_hi:[1, 0]
	v_add_u32_e32 v193, 2, v189
	v_cmp_gt_i32_e64 s[16:17], s10, v189
	s_and_saveexec_b64 s[10:11], s[16:17]
	s_cbranch_execz .Lupf_604
	v_cndmask_b32_e64 v93, v223, 0, vcc
	v_cndmask_b32_e64 v92, v222, 0, vcc
	v_pk_mul_f32 v[224:225], v[160:161], v[122:123]
	v_cndmask_b32_e64 v97, v221, 0, vcc
	v_cndmask_b32_e64 v96, v220, 0, vcc
	v_pk_fma_f32 v[92:93], v[92:93], v[106:107], v[224:225]
	v_pk_fma_f32 v[92:93], v[104:105], v[110:111], v[92:93]
	v_pk_add_f32 v[92:93], v[118:119], v[92:93]
	v_cndmask_b32_e64 v151, v151, 0, vcc
	v_pk_mul_f32 v[220:221], v[92:93], v[92:93]
	v_cndmask_b32_e64 v150, v150, 0, vcc
	v_fmamk_f32 v203, v220, 0xbdd2d3e8, v245
	v_mul_f32_e32 v203, v92, v203
	v_fmamk_f32 v220, v221, 0xbdd2d3e8, v245
	v_exp_f32_e32 v203, v203
	v_mul_f32_e32 v220, v93, v220
	v_exp_f32_e32 v225, v220
	v_pk_mul_f32 v[220:221], v[152:153], v[126:127]
	v_add_f32_e32 v203, 1.0, v203
	v_rcp_f32_e32 v224, v203
	v_add_f32_e32 v203, 1.0, v225
	v_rcp_f32_e32 v225, v203
	v_pk_fma_f32 v[96:97], v[96:97], v[114:115], v[220:221]
	v_pk_fma_f32 v[96:97], v[100:101], v[130:131], v[96:97]
	v_pk_mul_f32 v[92:93], v[92:93], v[224:225]
	v_pk_add_f32 v[96:97], v[138:139], v[96:97]
	v_pk_mul_f32 v[222:223], v[102:103], v[124:125]
	v_pk_mul_f32 v[92:93], v[96:97], v[92:93]
	v_cndmask_b32_e64 v97, v157, 0, vcc
	v_cndmask_b32_e64 v96, v156, 0, vcc
	v_pk_fma_f32 v[96:97], v[96:97], v[108:109], v[222:223]
	v_pk_fma_f32 v[96:97], v[94:95], v[112:113], v[96:97]
	v_cvt_pk_bf16_f32 v92, v92, v93
	v_pk_add_f32 v[96:97], v[120:121], v[96:97]
	s_nop 0
	v_pk_mul_f32 v[156:157], v[96:97], v[96:97]
	s_nop 0
	v_fmamk_f32 v156, v156, 0xbdd2d3e8, v245
	v_mul_f32_e32 v156, v96, v156
	v_exp_f32_e32 v203, v156
	v_fmamk_f32 v156, v157, 0xbdd2d3e8, v245
	v_mul_f32_e32 v156, v97, v156
	v_exp_f32_e32 v223, v156
	v_add_f32_e32 v203, 1.0, v203
	v_rcp_f32_e32 v222, v203
	v_pk_mul_f32 v[156:157], v[98:99], v[128:129]
	v_add_f32_e32 v203, 1.0, v223
	v_rcp_f32_e32 v223, v203
	v_pk_fma_f32 v[150:151], v[150:151], v[116:117], v[156:157]
	v_pk_mul_f32 v[96:97], v[96:97], v[222:223]
	v_pk_fma_f32 v[150:151], v[90:91], v[132:133], v[150:151]
	s_nop 0
	v_pk_add_f32 v[150:151], v[140:141], v[150:151]
	s_nop 0
	v_pk_mul_f32 v[96:97], v[150:151], v[96:97]
	s_nop 0
	v_cvt_pk_bf16_f32 v93, v96, v97
	v_mov_b64_e32 v[96:97], s[34:35]
	v_mad_i64_i32 v[96:97], s[12:13], v193, s85, v[96:97]
	v_lshl_add_u64 v[96:97], v[186:187], 1, v[96:97]
	global_store_dwordx2 v[96:97], v[92:93], off
;     __device__ __forceinline__ void operator()(const f32x4 (&acc)[2][2][4][2], const Unit& u, int wr, int wc, int fr, int fq) const {
;     ...
;                 for (int i = 0; i < 8; ++i) {
;                     float pg = i > 0 ? xg[i - 1] : gp, ng = i < 7 ? xg[i + 1] : gn, pv = i > 0 ? xv[i - 1] : vp, nv = i < 7 ? xv[i + 1] : vn;
;                     if (pz[i]) { pg = 0.f; pv = 0.f; } if (nz[i]) { ng = 0.f; nv = 0.f; }
;                     const float cgv = gw0 * pg + gw1 * xg[i] + gw2 * ng + gb;
;                     const float cvv = vw0 * pv + vw1 * xv[i] + vw2 * nv + vb;
;                     res[i][j] = gelu_tanh(cgv) * cvv;
;                 }
;             }
; #pragma unroll
;             for (int i = 0; i < 8; ++i) { const int s = 8 * fr + i, grow = grow0 + i;
;                 if (s >= 1 && s <= 126 && grow < HALF_TOK) { u32x2 w; w.x = pk2(res[i][0], res[i][1]); w.y = pk2(res[i][2], res[i][3]); *(u32x2*)(G + (size_t)grow * DFF + cg0 + 4 * n) = w; } }
.Lupf_604:
	s_or_b64 exec, exec, s[10:11]
	v_and_b32_e32 v92, 0x1fff, v201
	s_movk_i32 s12, 0x3ffd
	v_cmp_eq_u32_e64 s[10:11], 0, v92
	v_pk_mul_f32 v[96:97], v[86:87], v[192:193] op_sel_hi:[1, 0]
	v_pk_mul_f32 v[92:93], v[82:83], v[192:193] op_sel_hi:[1, 0]
	v_pk_mul_f32 v[86:87], v[88:89], v[192:193] op_sel_hi:[1, 0]
	v_pk_mul_f32 v[82:83], v[84:85], v[192:193] op_sel_hi:[1, 0]
	v_add_u32_e32 v150, 3, v189
	v_cmp_gt_i32_e64 s[18:19], s12, v189
	s_and_saveexec_b64 s[12:13], s[18:19]
	s_cbranch_execz .Lupf_606
	v_mov_b32_e32 v85, v161
	v_mov_b32_e32 v84, v160
	v_pk_mul_f32 v[160:161], v[104:105], v[122:123]
	v_mov_b32_e32 v89, v153
	v_mov_b32_e32 v88, v152
	v_pk_fma_f32 v[84:85], v[84:85], v[106:107], v[160:161]
	v_pk_fma_f32 v[84:85], v[96:97], v[110:111], v[84:85]
	v_pk_add_f32 v[84:85], v[118:119], v[84:85]
	v_pk_mul_f32 v[152:153], v[84:85], v[84:85]
	v_fmamk_f32 v151, v152, 0xbdd2d3e8, v245
	v_mul_f32_e32 v151, v84, v151
	v_fmamk_f32 v152, v153, 0xbdd2d3e8, v245
	v_exp_f32_e32 v151, v151
	v_mul_f32_e32 v152, v85, v152
	v_exp_f32_e32 v161, v152
	v_pk_mul_f32 v[152:153], v[100:101], v[126:127]
	v_add_f32_e32 v151, 1.0, v151
	v_rcp_f32_e32 v160, v151
	v_add_f32_e32 v151, 1.0, v161
	v_rcp_f32_e32 v161, v151
	v_pk_fma_f32 v[88:89], v[88:89], v[114:115], v[152:153]
	v_pk_fma_f32 v[88:89], v[92:93], v[130:131], v[88:89]
	v_pk_mul_f32 v[84:85], v[84:85], v[160:161]
	v_pk_add_f32 v[88:89], v[138:139], v[88:89]
	v_pk_mul_f32 v[156:157], v[94:95], v[124:125]
	v_pk_mul_f32 v[84:85], v[88:89], v[84:85]
	v_pk_fma_f32 v[88:89], v[102:103], v[108:109], v[156:157]
	v_pk_fma_f32 v[88:89], v[86:87], v[112:113], v[88:89]
	v_cvt_pk_bf16_f32 v84, v84, v85
	v_pk_add_f32 v[88:89], v[120:121], v[88:89]
	s_nop 0
	v_pk_mul_f32 v[102:103], v[88:89], v[88:89]
	s_nop 0
	v_fmamk_f32 v102, v102, 0xbdd2d3e8, v245
	v_mul_f32_e32 v102, v88, v102
	v_exp_f32_e32 v151, v102
	v_fmamk_f32 v102, v103, 0xbdd2d3e8, v245
	v_mul_f32_e32 v102, v89, v102
	v_exp_f32_e32 v157, v102
	v_add_f32_e32 v151, 1.0, v151
	v_rcp_f32_e32 v156, v151
	v_pk_mul_f32 v[102:103], v[90:91], v[128:129]
	v_add_f32_e32 v151, 1.0, v157
	v_rcp_f32_e32 v157, v151
	v_pk_fma_f32 v[98:99], v[98:99], v[116:117], v[102:103]
	v_pk_mul_f32 v[88:89], v[88:89], v[156:157]
	v_pk_fma_f32 v[98:99], v[82:83], v[132:133], v[98:99]
	s_nop 0
	v_pk_add_f32 v[98:99], v[140:141], v[98:99]
	s_nop 0
	v_pk_mul_f32 v[88:89], v[98:99], v[88:89]
	s_nop 0
	v_cvt_pk_bf16_f32 v85, v88, v89
	v_mov_b64_e32 v[88:89], s[34:35]
	v_mad_i64_i32 v[88:89], s[20:21], v150, s85, v[88:89]
	v_lshl_add_u64 v[88:89], v[186:187], 1, v[88:89]
	global_store_dwordx2 v[88:89], v[84:85], off
.Lupf_606:
	s_or_b64 exec, exec, s[12:13]
	v_and_b32_e32 v84, 0x1fff, v199
	v_cmp_eq_u32_e64 s[12:13], 0, v84
	v_cmp_ne_u32_e64 s[20:21], s67, v199
	s_and_b64 s[82:83], s[20:21], s[12:13]
	s_movk_i32 s12, 0x3ffc
	v_pk_mul_f32 v[88:89], v[78:79], v[190:191] op_sel_hi:[1, 0]
	v_pk_mul_f32 v[84:85], v[74:75], v[190:191] op_sel_hi:[1, 0]
	v_pk_mul_f32 v[78:79], v[80:81], v[190:191] op_sel_hi:[1, 0]
	v_pk_mul_f32 v[74:75], v[76:77], v[190:191] op_sel_hi:[1, 0]
	v_add_u32_e32 v151, 4, v189
	v_cmp_gt_i32_e64 s[20:21], s12, v189
	s_and_saveexec_b64 s[12:13], s[20:21]
	s_cbranch_execz .Lupf_608
	v_pk_mul_f32 v[102:103], v[96:97], v[122:123]
	v_pk_fma_f32 v[76:77], v[104:105], v[106:107], v[102:103]
	v_pk_fma_f32 v[76:77], v[88:89], v[110:111], v[76:77]
	v_pk_add_f32 v[76:77], v[118:119], v[76:77]
	v_pk_mul_f32 v[98:99], v[76:77], v[76:77]
	v_fmamk_f32 v98, v98, 0xbdd2d3e8, v245
	v_mul_f32_e32 v98, v76, v98
	v_exp_f32_e32 v102, v98
	v_fmamk_f32 v98, v99, 0xbdd2d3e8, v245
	v_mul_f32_e32 v98, v77, v98
	v_exp_f32_e32 v103, v98
	v_add_f32_e32 v102, 1.0, v102
	v_rcp_f32_e32 v102, v102
	v_pk_mul_f32 v[98:99], v[92:93], v[126:127]
	v_add_f32_e32 v103, 1.0, v103
	v_rcp_f32_e32 v103, v103
	v_pk_fma_f32 v[80:81], v[100:101], v[114:115], v[98:99]
	v_pk_fma_f32 v[80:81], v[84:85], v[130:131], v[80:81]
	v_pk_mul_f32 v[76:77], v[76:77], v[102:103]
	v_pk_add_f32 v[80:81], v[138:139], v[80:81]
	v_pk_mul_f32 v[100:101], v[86:87], v[124:125]
	v_pk_mul_f32 v[76:77], v[80:81], v[76:77]
	v_pk_fma_f32 v[80:81], v[94:95], v[108:109], v[100:101]
	v_pk_fma_f32 v[80:81], v[78:79], v[112:113], v[80:81]
	v_pk_add_f32 v[80:81], v[120:121], v[80:81]
	v_pk_mul_f32 v[94:95], v[80:81], v[80:81]
	v_cvt_pk_bf16_f32 v76, v76, v77
	v_fmamk_f32 v94, v94, 0xbdd2d3e8, v245
	v_mul_f32_e32 v94, v80, v94
	v_exp_f32_e32 v100, v94
	v_fmamk_f32 v94, v95, 0xbdd2d3e8, v245
	v_mul_f32_e32 v94, v81, v94
	v_exp_f32_e32 v101, v94
	v_add_f32_e32 v100, 1.0, v100
	v_rcp_f32_e32 v100, v100
	v_pk_mul_f32 v[94:95], v[82:83], v[128:129]
	v_add_f32_e32 v101, 1.0, v101
	v_rcp_f32_e32 v101, v101
	v_pk_fma_f32 v[90:91], v[90:91], v[116:117], v[94:95]
	v_pk_mul_f32 v[80:81], v[80:81], v[100:101]
	v_pk_fma_f32 v[90:91], v[74:75], v[132:133], v[90:91]
	s_nop 0
	v_pk_add_f32 v[90:91], v[140:141], v[90:91]
	s_nop 0
	v_pk_mul_f32 v[80:81], v[90:91], v[80:81]
	s_nop 0
	v_cvt_pk_bf16_f32 v77, v80, v81
	v_mov_b64_e32 v[80:81], s[34:35]
	v_mad_i64_i32 v[80:81], s[22:23], v151, s85, v[80:81]
	v_lshl_add_u64 v[80:81], v[186:187], 1, v[80:81]
	global_store_dwordx2 v[80:81], v[76:77], off
;     __device__ __forceinline__ void operator()(const f32x4 (&acc)[2][2][4][2], const Unit& u, int wr, int wc, int fr, int fq) const {
;     ...
;                 for (int i = 0; i < 8; ++i) {
;                     float pg = i > 0 ? xg[i - 1] : gp, ng = i < 7 ? xg[i + 1] : gn, pv = i > 0 ? xv[i - 1] : vp, nv = i < 7 ? xv[i + 1] : vn;
;                     if (pz[i]) { pg = 0.f; pv = 0.f; } if (nz[i]) { ng = 0.f; nv = 0.f; }
;                     const float cgv = gw0 * pg + gw1 * xg[i] + gw2 * ng + gb;
;                     const float cvv = vw0 * pv + vw1 * xv[i] + vw2 * nv + vb;
;                     res[i][j] = gelu_tanh(cgv) * cvv;
;                 }
;             }
; #pragma unroll
;             for (int i = 0; i < 8; ++i) { const int s = 8 * fr + i, grow = grow0 + i;
;                 if (s >= 1 && s <= 126 && grow < HALF_TOK) { u32x2 w; w.x = pk2(res[i][0], res[i][1]); w.y = pk2(res[i][2], res[i][3]); *(u32x2*)(G + (size_t)grow * DFF + cg0 + 4 * n) = w; } }
.Lupf_608:
	s_or_b64 exec, exec, s[12:13]
	v_and_b32_e32 v76, 0x1fff, v197
	s_movk_i32 s22, 0x3ffb
	v_cmp_eq_u32_e64 s[12:13], 0, v76
	v_pk_mul_f32 v[80:81], v[70:71], v[188:189] op_sel_hi:[1, 0]
	v_pk_mul_f32 v[76:77], v[66:67], v[188:189] op_sel_hi:[1, 0]
	v_pk_mul_f32 v[70:71], v[72:73], v[188:189] op_sel_hi:[1, 0]
	v_pk_mul_f32 v[66:67], v[68:69], v[188:189] op_sel_hi:[1, 0]
	v_add_u32_e32 v152, 5, v189
	v_cmp_gt_i32_e64 s[22:23], s22, v189
	s_and_saveexec_b64 s[24:25], s[22:23]
	s_cbranch_execz .Lupf_610
	v_pk_mul_f32 v[94:95], v[88:89], v[122:123]
	v_pk_fma_f32 v[68:69], v[96:97], v[106:107], v[94:95]
	v_pk_fma_f32 v[68:69], v[80:81], v[110:111], v[68:69]
	v_pk_add_f32 v[68:69], v[118:119], v[68:69]
	v_pk_mul_f32 v[94:95], v[84:85], v[126:127]
	v_pk_mul_f32 v[90:91], v[68:69], v[68:69]
	v_fmamk_f32 v90, v90, 0xbdd2d3e8, v245
	v_fmamk_f32 v91, v91, 0xbdd2d3e8, v245
	v_mul_f32_e32 v90, v68, v90
	v_mul_f32_e32 v91, v69, v91
	v_exp_f32_e32 v90, v90
	v_exp_f32_e32 v91, v91
	v_pk_fma_f32 v[72:73], v[92:93], v[114:115], v[94:95]
	v_add_f32_e32 v90, 1.0, v90
	v_add_f32_e32 v91, 1.0, v91
	v_rcp_f32_e32 v90, v90
	v_rcp_f32_e32 v91, v91
	v_pk_fma_f32 v[72:73], v[76:77], v[130:131], v[72:73]
	v_pk_mul_f32 v[92:93], v[78:79], v[124:125]
	v_pk_add_f32 v[72:73], v[138:139], v[72:73]
	v_pk_mul_f32 v[68:69], v[68:69], v[90:91]
	v_pk_mul_f32 v[68:69], v[72:73], v[68:69]
	v_pk_fma_f32 v[72:73], v[86:87], v[108:109], v[92:93]
	v_pk_fma_f32 v[72:73], v[70:71], v[112:113], v[72:73]
	v_pk_mul_f32 v[92:93], v[74:75], v[128:129]
	v_pk_add_f32 v[72:73], v[120:121], v[72:73]
	v_pk_mul_f32 v[86:87], v[72:73], v[72:73]
	v_fmamk_f32 v86, v86, 0xbdd2d3e8, v245
	v_fmamk_f32 v87, v87, 0xbdd2d3e8, v245
	v_mul_f32_e32 v86, v72, v86
	v_mul_f32_e32 v87, v73, v87
	v_exp_f32_e32 v86, v86
	v_exp_f32_e32 v87, v87
	v_pk_fma_f32 v[82:83], v[82:83], v[116:117], v[92:93]
	v_cvt_pk_bf16_f32 v68, v68, v69
	v_add_f32_e32 v86, 1.0, v86
	v_add_f32_e32 v87, 1.0, v87
	v_rcp_f32_e32 v86, v86
	v_rcp_f32_e32 v87, v87
	v_pk_fma_f32 v[82:83], v[66:67], v[132:133], v[82:83]
	v_pk_mul_f32 v[72:73], v[72:73], v[86:87]
	v_pk_add_f32 v[82:83], v[140:141], v[82:83]
	s_nop 0
	v_pk_mul_f32 v[72:73], v[82:83], v[72:73]
	s_nop 0
	v_cvt_pk_bf16_f32 v69, v72, v73
	v_mov_b64_e32 v[72:73], s[34:35]
	v_mad_i64_i32 v[72:73], s[28:29], v152, s85, v[72:73]
	v_lshl_add_u64 v[72:73], v[186:187], 1, v[72:73]
	global_store_dwordx2 v[72:73], v[68:69], off
.Lupf_610:
	s_or_b64 exec, exec, s[24:25]
	v_and_b32_e32 v68, 0x1fff, v195
	v_cmp_eq_u32_e64 s[24:25], 0, v68
	v_cmp_ne_u32_e64 s[28:29], s67, v195
	s_and_b64 s[86:87], s[28:29], s[24:25]
	s_movk_i32 s24, 0x3ffa
	v_add_u32_e32 v153, 6, v189
	v_cmp_gt_i32_e64 s[24:25], s24, v189
	s_and_saveexec_b64 s[28:29], s[24:25]
	s_cbranch_execz .Lupf_612
	v_pk_mul_f32 v[82:83], v[80:81], v[122:123]
	v_pk_fma_f32 v[68:69], v[88:89], v[106:107], v[82:83]
	v_pk_fma_f32 v[68:69], v[158:159], v[110:111], v[68:69]
	v_pk_add_f32 v[68:69], v[118:119], v[68:69]
	v_pk_mul_f32 v[86:87], v[76:77], v[126:127]
	v_pk_mul_f32 v[72:73], v[68:69], v[68:69]
	v_fmamk_f32 v72, v72, 0xbdd2d3e8, v245
	v_fmamk_f32 v73, v73, 0xbdd2d3e8, v245
	v_mul_f32_e32 v72, v68, v72
	v_mul_f32_e32 v73, v69, v73
	v_exp_f32_e32 v72, v72
	v_exp_f32_e32 v73, v73
	v_pk_fma_f32 v[82:83], v[84:85], v[114:115], v[86:87]
	v_add_f32_e32 v72, 1.0, v72
	v_add_f32_e32 v73, 1.0, v73
	v_rcp_f32_e32 v72, v72
	v_rcp_f32_e32 v73, v73
	v_pk_fma_f32 v[82:83], v[142:143], v[130:131], v[82:83]
	v_pk_mul_f32 v[84:85], v[70:71], v[124:125]
	v_pk_add_f32 v[82:83], v[138:139], v[82:83]
	v_pk_mul_f32 v[68:69], v[68:69], v[72:73]
	v_pk_fma_f32 v[72:73], v[78:79], v[108:109], v[84:85]
	v_pk_fma_f32 v[72:73], v[144:145], v[112:113], v[72:73]
	v_pk_add_f32 v[72:73], v[120:121], v[72:73]
	v_pk_mul_f32 v[84:85], v[66:67], v[128:129]
	v_pk_mul_f32 v[78:79], v[72:73], v[72:73]
	v_pk_mul_f32 v[68:69], v[82:83], v[68:69]
	v_fmamk_f32 v78, v78, 0xbdd2d3e8, v245
	v_fmamk_f32 v79, v79, 0xbdd2d3e8, v245
	v_mul_f32_e32 v78, v72, v78
	v_mul_f32_e32 v79, v73, v79
	v_exp_f32_e32 v78, v78
	v_exp_f32_e32 v79, v79
	v_add_f32_e32 v78, 1.0, v78
	v_add_f32_e32 v79, 1.0, v79
	v_rcp_f32_e32 v78, v78
	v_rcp_f32_e32 v79, v79
	v_pk_fma_f32 v[74:75], v[74:75], v[116:117], v[84:85]
	v_cvt_pk_bf16_f32 v68, v68, v69
	v_pk_fma_f32 v[74:75], v[134:135], v[132:133], v[74:75]
	v_pk_mul_f32 v[72:73], v[72:73], v[78:79]
	v_pk_add_f32 v[74:75], v[140:141], v[74:75]
	s_nop 0
	v_pk_mul_f32 v[72:73], v[74:75], v[72:73]
	s_nop 0
	v_cvt_pk_bf16_f32 v69, v72, v73
	v_mov_b64_e32 v[72:73], s[34:35]
	v_mad_i64_i32 v[72:73], s[68:69], v153, s85, v[72:73]
	v_lshl_add_u64 v[72:73], v[186:187], 1, v[72:73]
	global_store_dwordx2 v[72:73], v[68:69], off
;     __device__ __forceinline__ void operator()(const f32x4 (&acc)[2][2][4][2], const Unit& u, int wr, int wc, int fr, int fq) const {
;     ...
;             for (int j = 0; j < 4; ++j) {
;                 const int cg = cg0 + 4 * n + j;
;                 const float gw0 = cw[cg], gw1 = cw[NUP + cg], gw2 = cw[2 * NUP + cg], gb = cb[cg];
;                 const float vw0 = cw[DFF + cg], vw1 = cw[NUP + DFF + cg], vw2 = cw[2 * NUP + DFF + cg], vb = cb[DFF + cg];
;                 float xg[8], xv[8];
; #pragma unroll
;                 for (int i = 0; i < 8; ++i) { xg[i] = acc[i >> 2][0][i & 3][n][j] * rs[i]; xv[i] = acc[i >> 2][1][i & 3][n][j] * rs[i]; }
;                 const float gp = __builtin_bit_cast(float, __builtin_amdgcn_update_dpp(0, __builtin_bit_cast(int, xg[7]), 0x111, 0xf, 0xf, false));
;                 const float gn = __builtin_bit_cast(float, __builtin_amdgcn_update_dpp(0, __builtin_bit_cast(int, xg[0]), 0x101, 0xf, 0xf, false));
;                 const float vp = __builtin_bit_cast(float, __builtin_amdgcn_update_dpp(0, __builtin_bit_cast(int, xv[7]), 0x111, 0xf, 0xf, false));
;                 const float vn = __builtin_bit_cast(float, __builtin_amdgcn_update_dpp(0, __builtin_bit_cast(int, xv[0]), 0x101, 0xf, 0xf, false));
;     ...
;                 for (int i = 0; i < 8; ++i) {
;                     float pg = i > 0 ? xg[i - 1] : gp, ng = i < 7 ? xg[i + 1] : gn, pv = i > 0 ? xv[i - 1] : vp, nv = i < 7 ? xv[i + 1] : vn;
;                     if (pz[i]) { pg = 0.f; pv = 0.f; } if (nz[i]) { ng = 0.f; nv = 0.f; }
;                     const float cgv = gw0 * pg + gw1 * xg[i] + gw2 * ng + gb;
;                     const float cvv = vw0 * pv + vw1 * xv[i] + vw2 * nv + vb;
;                     res[i][j] = gelu_tanh(cgv) * cvv;
;                 }
;             }
; #pragma unroll
;             for (int i = 0; i < 8; ++i) { const int s = 8 * fr + i, grow = grow0 + i;
;                 if (s >= 1 && s <= 126 && grow < HALF_TOK) { u32x2 w; w.x = pk2(res[i][0], res[i][1]); w.y = pk2(res[i][2], res[i][3]); *(u32x2*)(G + (size_t)grow * DFF + cg0 + 4 * n) = w; } }
.Lupf_612:
	s_or_b64 exec, exec, s[28:29]
	s_movk_i32 s28, 0x3ff9
	v_cmp_gt_i32_e64 s[28:29], s28, v189
	v_add_u32_e32 v156, 7, v189
	s_and_b64 s[28:29], s[6:7], s[28:29]
	s_and_saveexec_b64 s[68:69], s[28:29]
	s_cbranch_execz .Lupf_614
	v_pk_mul_f32 v[72:73], v[158:159], v[122:123]
	v_pk_fma_f32 v[68:69], v[106:107], v[80:81], v[72:73]
	v_mov_b32_e32 v72, v76
	v_pk_fma_f32 v[68:69], v[110:111], v[154:155], v[68:69]
	v_mov_b32_e32 v73, v77
	v_pk_add_f32 v[68:69], v[118:119], v[68:69]
	v_pk_mul_f32 v[74:75], v[68:69], v[68:69]
	v_fmamk_f32 v74, v74, 0xbdd2d3e8, v245
	v_mul_f32_e32 v74, v68, v74
	v_exp_f32_e32 v76, v74
	v_fmamk_f32 v74, v75, 0xbdd2d3e8, v245
	v_mul_f32_e32 v74, v69, v74
	v_exp_f32_e32 v77, v74
	v_add_f32_e32 v76, 1.0, v76
	v_rcp_f32_e32 v76, v76
	v_pk_mul_f32 v[74:75], v[142:143], v[126:127]
	v_add_f32_e32 v77, 1.0, v77
	v_rcp_f32_e32 v77, v77
	v_pk_fma_f32 v[72:73], v[72:73], v[114:115], v[74:75]
	v_pk_fma_f32 v[72:73], v[130:131], v[146:147], v[72:73]
	v_pk_mul_f32 v[68:69], v[68:69], v[76:77]
	v_pk_add_f32 v[72:73], v[138:139], v[72:73]
	s_nop 0
	v_pk_mul_f32 v[68:69], v[72:73], v[68:69]
	v_pk_mul_f32 v[72:73], v[144:145], v[124:125]
	v_cvt_pk_bf16_f32 v68, v68, v69
	v_pk_fma_f32 v[70:71], v[70:71], v[108:109], v[72:73]
	s_nop 0
	v_pk_fma_f32 v[70:71], v[112:113], v[148:149], v[70:71]
	s_nop 0
	v_pk_add_f32 v[70:71], v[120:121], v[70:71]
	s_nop 0
	v_pk_mul_f32 v[72:73], v[70:71], v[70:71]
	s_nop 0
	v_fmamk_f32 v72, v72, 0xbdd2d3e8, v245
	v_mul_f32_e32 v72, v70, v72
	v_exp_f32_e32 v74, v72
	v_fmamk_f32 v72, v73, 0xbdd2d3e8, v245
	v_mul_f32_e32 v72, v71, v72
	v_exp_f32_e32 v75, v72
	v_add_f32_e32 v74, 1.0, v74
	v_rcp_f32_e32 v74, v74
	v_pk_mul_f32 v[72:73], v[134:135], v[128:129]
	v_add_f32_e32 v75, 1.0, v75
	v_rcp_f32_e32 v75, v75
	v_pk_fma_f32 v[66:67], v[66:67], v[116:117], v[72:73]
	v_pk_mul_f32 v[70:71], v[70:71], v[74:75]
	v_pk_fma_f32 v[66:67], v[132:133], v[136:137], v[66:67]
	s_nop 0
	v_pk_add_f32 v[66:67], v[140:141], v[66:67]
	s_nop 0
	v_pk_mul_f32 v[66:67], v[66:67], v[70:71]
	s_nop 0
	v_cvt_pk_bf16_f32 v69, v66, v67
	v_mov_b64_e32 v[66:67], s[34:35]
	v_mad_i64_i32 v[66:67], s[70:71], v156, s85, v[66:67]
	v_lshl_add_u64 v[66:67], v[186:187], 1, v[66:67]
	global_store_dwordx2 v[66:67], v[68:69], off
.Lupf_614:
	s_or_b64 exec, exec, s[68:69]
	v_mov_b32_e32 v203, v202
	v_mov_b32_e32 v201, v200
	v_mov_b32_e32 v199, v198
	global_load_dwordx4 v[70:73], v[206:207], off offset:16
	global_load_dwordx4 v[78:81], v[208:209], off offset:2064
	global_load_dwordx4 v[74:77], v[210:211], off offset:16
	global_load_dwordx4 v[82:85], v[204:205], off offset:16
	global_load_dwordx4 v[66:69], v[212:213], off offset:3088
	global_load_dwordx4 v[86:89], v[214:215], off offset:1040
	global_load_dwordx4 v[90:93], v[216:217], off offset:3088
	global_load_dwordx4 v[94:97], v[218:219], off offset:3088
	v_pk_mul_f32 v[98:99], v[46:47], v[202:203]
	v_mov_b32_e32 v112, 0
	v_pk_mul_f32 v[46:47], v[42:43], v[202:203]
	v_mov_b32_e32 v110, 0
	v_mov_b32_e32 v113, 0
	v_mov_b32_e32 v111, 0
	v_pk_mul_f32 v[102:103], v[58:59], v[200:201]
	v_pk_mul_f32 v[100:101], v[50:51], v[200:201]
	v_pk_mul_f32 v[108:109], v[62:63], v[198:199]
	v_mov_b32_e32 v58, 0
	v_pk_mul_f32 v[106:107], v[54:55], v[198:199]
	v_mov_b32_e32 v50, 0
	v_mov_b32_e32 v59, 0
	v_mov_b32_e32 v51, 0
	v_pk_mul_f32 v[48:49], v[48:49], v[202:203]
	v_mov_b32_e32 v114, 0
	v_pk_mul_f32 v[42:43], v[44:45], v[202:203]
	v_mov_b32_e32 v62, 0
	v_mov_b32_e32 v115, 0
	v_mov_b32_e32 v63, 0
	v_pk_mul_f32 v[54:55], v[52:53], v[200:201]
	v_pk_mul_f32 v[64:65], v[64:65], v[198:199]
	v_mov_b32_e32 v52, 0
	v_pk_mul_f32 v[104:105], v[56:57], v[198:199]
	v_mov_b32_e32 v44, 0
	v_mov_b32_e32 v53, 0
	v_mov_b32_e32 v45, 0
	v_mov_b32_dpp v112, v98 row_shr:1 row_mask:0xf bank_mask:0xf
	v_mov_b32_dpp v110, v46 row_shr:1 row_mask:0xf bank_mask:0xf
	v_mov_b32_dpp v113, v99 row_shr:1 row_mask:0xf bank_mask:0xf
	v_mov_b32_dpp v111, v47 row_shr:1 row_mask:0xf bank_mask:0xf
	v_mov_b32_dpp v58, v108 row_shl:1 row_mask:0xf bank_mask:0xf
	v_mov_b32_dpp v50, v106 row_shl:1 row_mask:0xf bank_mask:0xf
	v_mov_b32_dpp v59, v109 row_shl:1 row_mask:0xf bank_mask:0xf
	v_mov_b32_dpp v51, v107 row_shl:1 row_mask:0xf bank_mask:0xf
	v_mov_b32_dpp v114, v48 row_shr:1 row_mask:0xf bank_mask:0xf
	v_mov_b32_dpp v62, v42 row_shr:1 row_mask:0xf bank_mask:0xf
	v_mov_b32_dpp v115, v49 row_shr:1 row_mask:0xf bank_mask:0xf
	v_mov_b32_dpp v63, v43 row_shr:1 row_mask:0xf bank_mask:0xf
	v_pk_mul_f32 v[60:61], v[60:61], v[200:201]
	v_mov_b32_dpp v52, v64 row_shl:1 row_mask:0xf bank_mask:0xf
	v_mov_b32_dpp v44, v104 row_shl:1 row_mask:0xf bank_mask:0xf
	v_mov_b32_dpp v53, v65 row_shl:1 row_mask:0xf bank_mask:0xf
	v_mov_b32_dpp v45, v105 row_shl:1 row_mask:0xf bank_mask:0xf
	s_and_saveexec_b64 s[68:69], s[88:89]
	s_cbranch_execz .Lupf_616
	s_waitcnt vmcnt(7)
	v_pk_mul_f32 v[56:57], v[72:73], v[114:115]
	s_waitcnt vmcnt(6)
	v_pk_fma_f32 v[56:57], v[64:65], v[80:81], v[56:57]
	s_waitcnt vmcnt(5)
	v_pk_fma_f32 v[56:57], v[60:61], v[76:77], v[56:57]
	s_waitcnt vmcnt(3)
	v_pk_mul_f32 v[62:63], v[68:69], v[62:63]
	v_pk_add_f32 v[56:57], v[84:85], v[56:57]
	s_waitcnt vmcnt(2)
	v_pk_fma_f32 v[62:63], v[104:105], v[88:89], v[62:63]
	v_pk_mul_f32 v[114:115], v[56:57], v[56:57]
	v_fmamk_f32 v115, v115, 0xbdd2d3e8, v245
	v_fmamk_f32 v114, v114, 0xbdd2d3e8, v245
	v_mul_f32_e32 v115, v57, v115
	v_mul_f32_e32 v114, v56, v114
	v_pk_mul_f32 v[112:113], v[70:71], v[112:113]
	v_exp_f32_e32 v115, v115
	v_exp_f32_e32 v114, v114
	s_waitcnt vmcnt(1)
	v_pk_fma_f32 v[62:63], v[54:55], v[92:93], v[62:63]
	v_pk_fma_f32 v[112:113], v[108:109], v[78:79], v[112:113]
	v_pk_fma_f32 v[112:113], v[102:103], v[74:75], v[112:113]
	v_add_f32_e32 v115, 1.0, v115
	v_pk_add_f32 v[112:113], v[82:83], v[112:113]
	v_add_f32_e32 v114, 1.0, v114
	v_pk_mul_f32 v[116:117], v[112:113], v[112:113]
	v_rcp_f32_e32 v115, v115
	v_fmamk_f32 v117, v117, 0xbdd2d3e8, v245
	v_rcp_f32_e32 v114, v114
	v_mul_f32_e32 v117, v113, v117
	v_exp_f32_e32 v117, v117
	s_waitcnt vmcnt(0)
	v_pk_add_f32 v[62:63], v[96:97], v[62:63]
	v_pk_mul_f32 v[56:57], v[56:57], v[114:115]
	v_pk_mul_f32 v[110:111], v[66:67], v[110:111]
	v_pk_mul_f32 v[56:57], v[62:63], v[56:57]
	v_add_f32_e32 v62, 1.0, v117
	v_rcp_f32_e32 v63, v62
	v_fmamk_f32 v62, v116, 0xbdd2d3e8, v245
	v_mul_f32_e32 v62, v112, v62
	v_exp_f32_e32 v62, v62
	v_pk_fma_f32 v[110:111], v[106:107], v[86:87], v[110:111]
	v_add_f32_e32 v62, 1.0, v62
	v_rcp_f32_e32 v62, v62
	v_pk_fma_f32 v[110:111], v[100:101], v[90:91], v[110:111]
	v_pk_mul_f32 v[62:63], v[112:113], v[62:63]
	v_pk_add_f32 v[110:111], v[94:95], v[110:111]
	s_nop 0
	v_pk_mul_f32 v[62:63], v[110:111], v[62:63]
	s_nop 0
	v_cvt_pk_bf16_f32 v62, v62, v63
	v_cvt_pk_bf16_f32 v63, v56, v57
	v_mov_b64_e32 v[56:57], s[34:35]
	v_mad_i64_i32 v[56:57], s[70:71], v189, s85, v[56:57]
	v_lshl_add_u64 v[56:57], v[186:187], 1, v[56:57]
	global_store_dwordx2 v[56:57], v[62:63], off offset:8
;     __device__ __forceinline__ void operator()(const f32x4 (&acc)[2][2][4][2], const Unit& u, int wr, int wc, int fr, int fq) const {
;     ...
;                 for (int i = 0; i < 8; ++i) {
;                     float pg = i > 0 ? xg[i - 1] : gp, ng = i < 7 ? xg[i + 1] : gn, pv = i > 0 ? xv[i - 1] : vp, nv = i < 7 ? xv[i + 1] : vn;
;                     if (pz[i]) { pg = 0.f; pv = 0.f; } if (nz[i]) { ng = 0.f; nv = 0.f; }
;                     const float cgv = gw0 * pg + gw1 * xg[i] + gw2 * ng + gb;
;                     const float cvv = vw0 * pv + vw1 * xv[i] + vw2 * nv + vb;
;                     res[i][j] = gelu_tanh(cgv) * cvv;
;                 }
;             }
; #pragma unroll
;             for (int i = 0; i < 8; ++i) { const int s = 8 * fr + i, grow = grow0 + i;
;                 if (s >= 1 && s <= 126 && grow < HALF_TOK) { u32x2 w; w.x = pk2(res[i][0], res[i][1]); w.y = pk2(res[i][2], res[i][3]); *(u32x2*)(G + (size_t)grow * DFF + cg0 + 4 * n) = w; } }
.Lupf_616:
	s_or_b64 exec, exec, s[68:69]
	v_mov_b32_e32 v197, v196
	v_pk_mul_f32 v[62:63], v[38:39], v[196:197]
	v_pk_mul_f32 v[56:57], v[34:35], v[196:197]
	v_pk_mul_f32 v[38:39], v[40:41], v[196:197]
	v_pk_mul_f32 v[34:35], v[36:37], v[196:197]
	s_and_saveexec_b64 s[88:89], s[14:15]
	s_cbranch_execz .Lupf_618
	s_waitcnt vmcnt(6)
	v_pk_mul_f32 v[110:111], v[102:103], v[78:79]
	v_mov_b32_e32 v41, v107
	v_mov_b32_e32 v40, v106
	v_cndmask_b32_e64 v107, v63, 0, vcc
	v_cndmask_b32_e64 v106, v62, 0, vcc
	v_pk_fma_f32 v[36:37], v[108:109], v[70:71], v[110:111]
	v_cndmask_b32_e64 v109, v57, 0, vcc
	s_waitcnt vmcnt(5)
	v_pk_fma_f32 v[36:37], v[106:107], v[74:75], v[36:37]
	v_cndmask_b32_e64 v108, v56, 0, vcc
	s_waitcnt vmcnt(4)
	v_pk_add_f32 v[36:37], v[82:83], v[36:37]
	s_nop 0
	v_pk_mul_f32 v[106:107], v[36:37], v[36:37]
	s_nop 0
	v_fmamk_f32 v106, v106, 0xbdd2d3e8, v245
	v_mul_f32_e32 v106, v36, v106
	v_exp_f32_e32 v110, v106
	v_fmamk_f32 v106, v107, 0xbdd2d3e8, v245
	v_mul_f32_e32 v106, v37, v106
	v_exp_f32_e32 v111, v106
	v_add_f32_e32 v110, 1.0, v110
	v_rcp_f32_e32 v110, v110
	s_waitcnt vmcnt(2)
	v_pk_mul_f32 v[106:107], v[100:101], v[86:87]
	v_add_f32_e32 v111, 1.0, v111
	v_rcp_f32_e32 v111, v111
	v_pk_fma_f32 v[40:41], v[40:41], v[66:67], v[106:107]
	v_cndmask_b32_e64 v107, v35, 0, vcc
	s_waitcnt vmcnt(1)
	v_pk_fma_f32 v[40:41], v[108:109], v[90:91], v[40:41]
	v_pk_mul_f32 v[36:37], v[36:37], v[110:111]
	s_waitcnt vmcnt(0)
	v_pk_add_f32 v[40:41], v[94:95], v[40:41]
	v_pk_mul_f32 v[108:109], v[60:61], v[80:81]
	v_pk_mul_f32 v[36:37], v[40:41], v[36:37]
	v_mov_b32_e32 v41, v65
	v_mov_b32_e32 v40, v64
	v_mov_b32_e32 v65, v105
	v_mov_b32_e32 v64, v104
	v_cndmask_b32_e64 v105, v39, 0, vcc
	v_cndmask_b32_e64 v104, v38, 0, vcc
	v_pk_fma_f32 v[40:41], v[40:41], v[72:73], v[108:109]
	v_cndmask_b32_e64 v106, v34, 0, vcc
	v_pk_fma_f32 v[40:41], v[104:105], v[76:77], v[40:41]
	v_cvt_pk_bf16_f32 v36, v36, v37
	v_pk_add_f32 v[40:41], v[84:85], v[40:41]
	s_nop 0
	v_pk_mul_f32 v[104:105], v[40:41], v[40:41]
	s_nop 0
	v_fmamk_f32 v104, v104, 0xbdd2d3e8, v245
	v_mul_f32_e32 v104, v40, v104
	v_exp_f32_e32 v108, v104
	v_fmamk_f32 v104, v105, 0xbdd2d3e8, v245
	v_mul_f32_e32 v104, v41, v104
	v_exp_f32_e32 v109, v104
	v_add_f32_e32 v108, 1.0, v108
	v_rcp_f32_e32 v108, v108
	v_pk_mul_f32 v[104:105], v[54:55], v[88:89]
	v_add_f32_e32 v109, 1.0, v109
	v_rcp_f32_e32 v109, v109
	v_pk_fma_f32 v[64:65], v[64:65], v[68:69], v[104:105]
	v_pk_mul_f32 v[40:41], v[40:41], v[108:109]
	v_pk_fma_f32 v[64:65], v[106:107], v[92:93], v[64:65]
	s_nop 0
	v_pk_add_f32 v[64:65], v[96:97], v[64:65]
	s_nop 0
	v_pk_mul_f32 v[40:41], v[64:65], v[40:41]
	s_nop 0
	v_cvt_pk_bf16_f32 v37, v40, v41
	v_mov_b64_e32 v[40:41], s[34:35]
	v_mad_i64_i32 v[40:41], s[14:15], v191, s85, v[40:41]
	v_lshl_add_u64 v[40:41], v[186:187], 1, v[40:41]
	global_store_dwordx2 v[40:41], v[36:37], off offset:8
.Lupf_618:
	s_or_b64 exec, exec, s[88:89]
	v_mov_b32_e32 v195, v194
	v_pk_mul_f32 v[40:41], v[30:31], v[194:195]
	v_pk_mul_f32 v[36:37], v[26:27], v[194:195]
	v_pk_mul_f32 v[30:31], v[32:33], v[194:195]
	v_pk_mul_f32 v[26:27], v[28:29], v[194:195]
	s_and_saveexec_b64 s[14:15], s[16:17]
	s_cbranch_execz .Lupf_620
	v_cndmask_b32_e64 v29, v103, 0, vcc
	v_cndmask_b32_e64 v28, v102, 0, vcc
	s_waitcnt vmcnt(6)
	v_pk_mul_f32 v[102:103], v[62:63], v[78:79]
	v_pk_fma_f32 v[28:29], v[28:29], v[70:71], v[102:103]
	v_cndmask_b32_e64 v33, v101, 0, vcc
	s_waitcnt vmcnt(5)
	v_pk_fma_f32 v[28:29], v[40:41], v[74:75], v[28:29]
	v_cndmask_b32_e64 v32, v100, 0, vcc
	s_waitcnt vmcnt(4)
	v_pk_add_f32 v[28:29], v[82:83], v[28:29]
	v_pk_mul_f32 v[64:65], v[28:29], v[28:29]
	v_fmamk_f32 v64, v64, 0xbdd2d3e8, v245
	v_mul_f32_e32 v64, v28, v64
	v_exp_f32_e32 v102, v64
	v_fmamk_f32 v64, v65, 0xbdd2d3e8, v245
	v_mul_f32_e32 v64, v29, v64
	v_exp_f32_e32 v103, v64
	v_add_f32_e32 v102, 1.0, v102
	v_rcp_f32_e32 v102, v102
	s_waitcnt vmcnt(2)
	v_pk_mul_f32 v[64:65], v[56:57], v[86:87]
	v_add_f32_e32 v103, 1.0, v103
	v_rcp_f32_e32 v103, v103
	v_pk_fma_f32 v[32:33], v[32:33], v[66:67], v[64:65]
	v_cndmask_b32_e64 v55, v55, 0, vcc
	s_waitcnt vmcnt(1)
	v_pk_fma_f32 v[32:33], v[36:37], v[90:91], v[32:33]
	v_pk_mul_f32 v[28:29], v[28:29], v[102:103]
	s_waitcnt vmcnt(0)
	v_pk_add_f32 v[32:33], v[94:95], v[32:33]
	v_pk_mul_f32 v[100:101], v[38:39], v[80:81]
	v_pk_mul_f32 v[28:29], v[32:33], v[28:29]
	v_cndmask_b32_e64 v33, v61, 0, vcc
	v_cndmask_b32_e64 v32, v60, 0, vcc
	v_pk_fma_f32 v[32:33], v[32:33], v[72:73], v[100:101]
	v_cndmask_b32_e64 v54, v54, 0, vcc
	v_pk_fma_f32 v[32:33], v[30:31], v[76:77], v[32:33]
	v_pk_add_f32 v[32:33], v[84:85], v[32:33]
	v_pk_mul_f32 v[60:61], v[32:33], v[32:33]
	v_cvt_pk_bf16_f32 v28, v28, v29
	v_fmamk_f32 v60, v60, 0xbdd2d3e8, v245
	v_mul_f32_e32 v60, v32, v60
	v_exp_f32_e32 v100, v60
	v_fmamk_f32 v60, v61, 0xbdd2d3e8, v245
	v_mul_f32_e32 v60, v33, v60
	v_exp_f32_e32 v101, v60
	v_add_f32_e32 v100, 1.0, v100
	v_rcp_f32_e32 v100, v100
	v_pk_mul_f32 v[60:61], v[34:35], v[88:89]
	v_add_f32_e32 v101, 1.0, v101
	v_rcp_f32_e32 v101, v101
	v_pk_fma_f32 v[54:55], v[54:55], v[68:69], v[60:61]
	v_pk_mul_f32 v[32:33], v[32:33], v[100:101]
	v_pk_fma_f32 v[54:55], v[26:27], v[92:93], v[54:55]
	s_nop 0
	v_pk_add_f32 v[54:55], v[96:97], v[54:55]
	s_nop 0
	v_pk_mul_f32 v[32:33], v[54:55], v[32:33]
	s_nop 0
	v_cvt_pk_bf16_f32 v29, v32, v33
	v_mov_b64_e32 v[32:33], s[34:35]
	v_mad_i64_i32 v[32:33], s[16:17], v193, s85, v[32:33]
	v_lshl_add_u64 v[32:33], v[186:187], 1, v[32:33]
	global_store_dwordx2 v[32:33], v[28:29], off offset:8
;     __device__ __forceinline__ void operator()(const f32x4 (&acc)[2][2][4][2], const Unit& u, int wr, int wc, int fr, int fq) const {
;     ...
;                 for (int i = 0; i < 8; ++i) {
;                     float pg = i > 0 ? xg[i - 1] : gp, ng = i < 7 ? xg[i + 1] : gn, pv = i > 0 ? xv[i - 1] : vp, nv = i < 7 ? xv[i + 1] : vn;
;                     if (pz[i]) { pg = 0.f; pv = 0.f; } if (nz[i]) { ng = 0.f; nv = 0.f; }
;                     const float cgv = gw0 * pg + gw1 * xg[i] + gw2 * ng + gb;
;                     const float cvv = vw0 * pv + vw1 * xv[i] + vw2 * nv + vb;
;                     res[i][j] = gelu_tanh(cgv) * cvv;
;                 }
;             }
; #pragma unroll
;             for (int i = 0; i < 8; ++i) { const int s = 8 * fr + i, grow = grow0 + i;
;                 if (s >= 1 && s <= 126 && grow < HALF_TOK) { u32x2 w; w.x = pk2(res[i][0], res[i][1]); w.y = pk2(res[i][2], res[i][3]); *(u32x2*)(G + (size_t)grow * DFF + cg0 + 4 * n) = w; } }
.Lupf_620:
	s_or_b64 exec, exec, s[14:15]
	v_mov_b32_e32 v193, v192
	v_pk_mul_f32 v[32:33], v[22:23], v[192:193]
	v_pk_mul_f32 v[28:29], v[18:19], v[192:193]
	v_pk_mul_f32 v[22:23], v[24:25], v[192:193]
	v_pk_mul_f32 v[18:19], v[20:21], v[192:193]
	s_and_saveexec_b64 s[14:15], s[18:19]
	s_cbranch_execz .Lupf_622
	s_waitcnt vmcnt(6)
	v_pk_mul_f32 v[60:61], v[40:41], v[78:79]
	v_pk_fma_f32 v[20:21], v[62:63], v[70:71], v[60:61]
	s_waitcnt vmcnt(5)
	v_pk_fma_f32 v[20:21], v[32:33], v[74:75], v[20:21]
	s_waitcnt vmcnt(4)
	v_pk_add_f32 v[20:21], v[82:83], v[20:21]
	v_pk_mul_f32 v[54:55], v[20:21], v[20:21]
	v_fmamk_f32 v54, v54, 0xbdd2d3e8, v245
	v_mul_f32_e32 v54, v20, v54
	v_exp_f32_e32 v60, v54
	v_fmamk_f32 v54, v55, 0xbdd2d3e8, v245
	v_mul_f32_e32 v54, v21, v54
	v_exp_f32_e32 v61, v54
	v_add_f32_e32 v60, 1.0, v60
	v_rcp_f32_e32 v60, v60
	s_waitcnt vmcnt(2)
	v_pk_mul_f32 v[54:55], v[36:37], v[86:87]
	v_add_f32_e32 v61, 1.0, v61
	v_rcp_f32_e32 v61, v61
	v_pk_fma_f32 v[24:25], v[56:57], v[66:67], v[54:55]
	s_waitcnt vmcnt(1)
	v_pk_fma_f32 v[24:25], v[28:29], v[90:91], v[24:25]
	v_pk_mul_f32 v[20:21], v[20:21], v[60:61]
	s_waitcnt vmcnt(0)
	v_pk_add_f32 v[24:25], v[94:95], v[24:25]
	v_pk_mul_f32 v[56:57], v[30:31], v[80:81]
	v_pk_mul_f32 v[20:21], v[24:25], v[20:21]
	v_pk_fma_f32 v[24:25], v[38:39], v[72:73], v[56:57]
	v_pk_fma_f32 v[24:25], v[22:23], v[76:77], v[24:25]
	v_pk_add_f32 v[24:25], v[84:85], v[24:25]
	v_pk_mul_f32 v[38:39], v[24:25], v[24:25]
	v_cvt_pk_bf16_f32 v20, v20, v21
	v_fmamk_f32 v38, v38, 0xbdd2d3e8, v245
	v_mul_f32_e32 v38, v24, v38
	v_exp_f32_e32 v56, v38
	v_fmamk_f32 v38, v39, 0xbdd2d3e8, v245
	v_mul_f32_e32 v38, v25, v38
	v_exp_f32_e32 v57, v38
	v_add_f32_e32 v56, 1.0, v56
	v_rcp_f32_e32 v56, v56
	v_pk_mul_f32 v[38:39], v[26:27], v[88:89]
	v_add_f32_e32 v57, 1.0, v57
	v_rcp_f32_e32 v57, v57
	v_pk_fma_f32 v[34:35], v[34:35], v[68:69], v[38:39]
	v_pk_mul_f32 v[24:25], v[24:25], v[56:57]
	v_pk_fma_f32 v[34:35], v[18:19], v[92:93], v[34:35]
	s_nop 0
	v_pk_add_f32 v[34:35], v[96:97], v[34:35]
	s_nop 0
	v_pk_mul_f32 v[24:25], v[34:35], v[24:25]
	s_nop 0
	v_cvt_pk_bf16_f32 v21, v24, v25
	v_mov_b64_e32 v[24:25], s[34:35]
	v_mad_i64_i32 v[24:25], s[16:17], v150, s85, v[24:25]
	v_lshl_add_u64 v[24:25], v[186:187], 1, v[24:25]
	global_store_dwordx2 v[24:25], v[20:21], off offset:8
.Lupf_622:
	s_or_b64 exec, exec, s[14:15]
	v_mov_b32_e32 v191, v190
	v_pk_mul_f32 v[24:25], v[14:15], v[190:191]
	v_pk_mul_f32 v[20:21], v[10:11], v[190:191]
	v_pk_mul_f32 v[14:15], v[16:17], v[190:191]
	v_pk_mul_f32 v[10:11], v[12:13], v[190:191]
	s_and_saveexec_b64 s[14:15], s[20:21]
	s_cbranch_execz .Lupf_624
	s_waitcnt vmcnt(6)
	v_pk_mul_f32 v[38:39], v[32:33], v[78:79]
	v_pk_fma_f32 v[12:13], v[40:41], v[70:71], v[38:39]
	s_waitcnt vmcnt(5)
	v_pk_fma_f32 v[12:13], v[24:25], v[74:75], v[12:13]
	s_waitcnt vmcnt(4)
	v_pk_add_f32 v[12:13], v[82:83], v[12:13]
	v_pk_mul_f32 v[34:35], v[12:13], v[12:13]
	v_fmamk_f32 v34, v34, 0xbdd2d3e8, v245
	v_mul_f32_e32 v34, v12, v34
	v_exp_f32_e32 v38, v34
	v_fmamk_f32 v34, v35, 0xbdd2d3e8, v245
	v_mul_f32_e32 v34, v13, v34
	v_exp_f32_e32 v39, v34
	v_add_f32_e32 v38, 1.0, v38
	v_rcp_f32_e32 v38, v38
	s_waitcnt vmcnt(2)
	v_pk_mul_f32 v[34:35], v[28:29], v[86:87]
	v_add_f32_e32 v39, 1.0, v39
	v_rcp_f32_e32 v39, v39
	v_pk_fma_f32 v[16:17], v[36:37], v[66:67], v[34:35]
	s_waitcnt vmcnt(1)
	v_pk_fma_f32 v[16:17], v[20:21], v[90:91], v[16:17]
	v_pk_mul_f32 v[12:13], v[12:13], v[38:39]
	s_waitcnt vmcnt(0)
	v_pk_add_f32 v[16:17], v[94:95], v[16:17]
	v_pk_mul_f32 v[36:37], v[22:23], v[80:81]
	v_pk_mul_f32 v[12:13], v[16:17], v[12:13]
	v_pk_fma_f32 v[16:17], v[30:31], v[72:73], v[36:37]
	v_pk_fma_f32 v[16:17], v[14:15], v[76:77], v[16:17]
	v_pk_add_f32 v[16:17], v[84:85], v[16:17]
	v_pk_mul_f32 v[30:31], v[16:17], v[16:17]
	v_cvt_pk_bf16_f32 v12, v12, v13
	v_fmamk_f32 v30, v30, 0xbdd2d3e8, v245
	v_mul_f32_e32 v30, v16, v30
	v_exp_f32_e32 v36, v30
	v_fmamk_f32 v30, v31, 0xbdd2d3e8, v245
	v_mul_f32_e32 v30, v17, v30
	v_exp_f32_e32 v37, v30
	v_add_f32_e32 v36, 1.0, v36
	v_rcp_f32_e32 v36, v36
	v_pk_mul_f32 v[30:31], v[18:19], v[88:89]
	v_add_f32_e32 v37, 1.0, v37
	v_rcp_f32_e32 v37, v37
	v_pk_fma_f32 v[26:27], v[26:27], v[68:69], v[30:31]
	v_pk_mul_f32 v[16:17], v[16:17], v[36:37]
	v_pk_fma_f32 v[26:27], v[10:11], v[92:93], v[26:27]
	s_nop 0
	v_pk_add_f32 v[26:27], v[96:97], v[26:27]
	s_nop 0
	v_pk_mul_f32 v[16:17], v[26:27], v[16:17]
	s_nop 0
	v_cvt_pk_bf16_f32 v13, v16, v17
	v_mov_b64_e32 v[16:17], s[34:35]
	v_mad_i64_i32 v[16:17], s[10:11], v151, s85, v[16:17]
	v_lshl_add_u64 v[16:17], v[186:187], 1, v[16:17]
	global_store_dwordx2 v[16:17], v[12:13], off offset:8

;     __device__ __forceinline__ void operator()(const f32x4 (&acc)[2][2][4][2], const Unit& u, int wr, int wc, int fr, int fq) const {
;     ...
;                 for (int i = 0; i < 8; ++i) {
;                     float pg = i > 0 ? xg[i - 1] : gp, ng = i < 7 ? xg[i + 1] : gn, pv = i > 0 ? xv[i - 1] : vp, nv = i < 7 ? xv[i + 1] : vn;
;                     if (pz[i]) { pg = 0.f; pv = 0.f; } if (nz[i]) { ng = 0.f; nv = 0.f; }
;                     const float cgv = gw0 * pg + gw1 * xg[i] + gw2 * ng + gb;
;                     const float cvv = vw0 * pv + vw1 * xv[i] + vw2 * nv + vb;
;                     res[i][j] = gelu_tanh(cgv) * cvv;
;                 }
;             }
; #pragma unroll
;             for (int i = 0; i < 8; ++i) { const int s = 8 * fr + i, grow = grow0 + i;
;                 if (s >= 1 && s <= 126 && grow < HALF_TOK) { u32x2 w; w.x = pk2(res[i][0], res[i][1]); w.y = pk2(res[i][2], res[i][3]); *(u32x2*)(G + (size_t)grow * DFF + cg0 + 4 * n) = w; } }
.Lupf_627:
	s_waitcnt vmcnt(6)
	v_pk_mul_f32 v[8:9], v[98:99], v[78:79]
	v_pk_fma_f32 v[4:5], v[16:17], v[70:71], v[8:9]
	v_mov_b32_e32 v8, v12
	s_waitcnt vmcnt(5)
	v_pk_fma_f32 v[4:5], v[74:75], v[58:59], v[4:5]
	v_mov_b32_e32 v9, v13
	s_waitcnt vmcnt(4)
	v_pk_add_f32 v[4:5], v[82:83], v[4:5]
	v_pk_mul_f32 v[10:11], v[4:5], v[4:5]
	v_fmamk_f32 v10, v10, 0xbdd2d3e8, v245
	v_mul_f32_e32 v10, v4, v10
	v_exp_f32_e32 v12, v10
	v_fmamk_f32 v10, v11, 0xbdd2d3e8, v245
	v_mul_f32_e32 v10, v5, v10
	v_exp_f32_e32 v13, v10
	v_add_f32_e32 v12, 1.0, v12
	v_rcp_f32_e32 v12, v12
	s_waitcnt vmcnt(2)
	v_pk_mul_f32 v[10:11], v[46:47], v[86:87]
	v_add_f32_e32 v13, 1.0, v13
	v_rcp_f32_e32 v13, v13
	v_pk_fma_f32 v[8:9], v[8:9], v[66:67], v[10:11]
	s_waitcnt vmcnt(1)
	v_pk_fma_f32 v[8:9], v[90:91], v[50:51], v[8:9]
	v_pk_mul_f32 v[4:5], v[4:5], v[12:13]
	s_waitcnt vmcnt(0)
	v_pk_add_f32 v[8:9], v[94:95], v[8:9]
	s_nop 0
	v_pk_mul_f32 v[4:5], v[8:9], v[4:5]
	v_pk_mul_f32 v[8:9], v[48:49], v[80:81]
	v_cvt_pk_bf16_f32 v4, v4, v5
	v_pk_fma_f32 v[6:7], v[6:7], v[72:73], v[8:9]
	s_nop 0
	v_pk_fma_f32 v[6:7], v[76:77], v[52:53], v[6:7]
	s_nop 0
	v_pk_add_f32 v[6:7], v[84:85], v[6:7]
	s_nop 0
	v_pk_mul_f32 v[8:9], v[6:7], v[6:7]
	s_nop 0
	v_fmamk_f32 v8, v8, 0xbdd2d3e8, v245
	v_mul_f32_e32 v8, v6, v8
	v_exp_f32_e32 v10, v8
	v_fmamk_f32 v8, v9, 0xbdd2d3e8, v245
	v_mul_f32_e32 v8, v7, v8
	v_exp_f32_e32 v11, v8
	v_add_f32_e32 v10, 1.0, v10
	v_rcp_f32_e32 v10, v10
	v_pk_mul_f32 v[8:9], v[42:43], v[88:89]
	v_add_f32_e32 v11, 1.0, v11
	v_rcp_f32_e32 v11, v11
	v_pk_fma_f32 v[2:3], v[2:3], v[68:69], v[8:9]
	v_pk_mul_f32 v[6:7], v[6:7], v[10:11]
	v_pk_fma_f32 v[2:3], v[92:93], v[44:45], v[2:3]
	s_nop 0
	v_pk_add_f32 v[2:3], v[96:97], v[2:3]
	s_nop 0
	v_pk_mul_f32 v[2:3], v[2:3], v[6:7]
	s_nop 0
	v_cvt_pk_bf16_f32 v5, v2, v3
	v_mov_b64_e32 v[2:3], s[34:35]
	v_mad_i64_i32 v[2:3], s[12:13], v156, s85, v[2:3]
	v_lshl_add_u64 v[2:3], v[186:187], 1, v[2:3]
	global_store_dwordx2 v[2:3], v[4:5], off offset:8

;     __device__ __forceinline__ void operator()(const f32x4 (&acc)[2][2][4][2], const Unit& u, int wr, int wc, int fr, int fq) const {
;     ...
;                 for (int i = 0; i < 8; ++i) {
;                     float pg = i > 0 ? xg[i - 1] : gp, ng = i < 7 ? xg[i + 1] : gn, pv = i > 0 ? xv[i - 1] : vp, nv = i < 7 ? xv[i + 1] : vn;
;                     if (pz[i]) { pg = 0.f; pv = 0.f; } if (nz[i]) { ng = 0.f; nv = 0.f; }
;                     const float cgv = gw0 * pg + gw1 * xg[i] + gw2 * ng + gb;
;                     const float cvv = vw0 * pv + vw1 * xv[i] + vw2 * nv + vb;
;                     res[i][j] = gelu_tanh(cgv) * cvv;
;                 }
;             }
; #pragma unroll
;             for (int i = 0; i < 8; ++i) { const int s = 8 * fr + i, grow = grow0 + i;
;                 if (s >= 1 && s <= 126 && grow < HALF_TOK) { u32x2 w; w.x = pk2(res[i][0], res[i][1]); w.y = pk2(res[i][2], res[i][3]); *(u32x2*)(G + (size_t)grow * DFF + cg0 + 4 * n) = w; } }
.Lupf_631:
	s_waitcnt vmcnt(6)
	v_pk_mul_f32 v[30:31], v[24:25], v[78:79]
	v_pk_fma_f32 v[4:5], v[32:33], v[70:71], v[30:31]
	s_waitcnt vmcnt(5)
	v_pk_fma_f32 v[4:5], v[16:17], v[74:75], v[4:5]
	s_waitcnt vmcnt(4)
	v_pk_add_f32 v[4:5], v[82:83], v[4:5]
	s_waitcnt vmcnt(2)
	v_pk_mul_f32 v[30:31], v[20:21], v[86:87]
	v_pk_mul_f32 v[26:27], v[4:5], v[4:5]
	v_fmamk_f32 v26, v26, 0xbdd2d3e8, v245
	v_fmamk_f32 v27, v27, 0xbdd2d3e8, v245
	v_mul_f32_e32 v26, v4, v26
	v_mul_f32_e32 v27, v5, v27
	v_exp_f32_e32 v26, v26
	v_exp_f32_e32 v27, v27
	v_pk_fma_f32 v[8:9], v[28:29], v[66:67], v[30:31]
	v_add_f32_e32 v26, 1.0, v26
	v_add_f32_e32 v27, 1.0, v27
	v_rcp_f32_e32 v26, v26
	v_rcp_f32_e32 v27, v27
	s_waitcnt vmcnt(1)
	v_pk_fma_f32 v[8:9], v[12:13], v[90:91], v[8:9]
	v_pk_mul_f32 v[28:29], v[14:15], v[80:81]
	s_waitcnt vmcnt(0)
	v_pk_add_f32 v[8:9], v[94:95], v[8:9]
	v_pk_mul_f32 v[4:5], v[4:5], v[26:27]
	v_pk_mul_f32 v[4:5], v[8:9], v[4:5]
	v_pk_fma_f32 v[8:9], v[22:23], v[72:73], v[28:29]
	v_pk_fma_f32 v[8:9], v[6:7], v[76:77], v[8:9]
	v_pk_mul_f32 v[28:29], v[10:11], v[88:89]
	v_pk_add_f32 v[8:9], v[84:85], v[8:9]
	v_pk_mul_f32 v[22:23], v[8:9], v[8:9]
	v_fmamk_f32 v22, v22, 0xbdd2d3e8, v245
	v_fmamk_f32 v23, v23, 0xbdd2d3e8, v245
	v_mul_f32_e32 v22, v8, v22
	v_mul_f32_e32 v23, v9, v23
	v_exp_f32_e32 v22, v22
	v_exp_f32_e32 v23, v23
	v_pk_fma_f32 v[18:19], v[18:19], v[68:69], v[28:29]
	v_cvt_pk_bf16_f32 v4, v4, v5
	v_add_f32_e32 v22, 1.0, v22
	v_add_f32_e32 v23, 1.0, v23
	v_rcp_f32_e32 v22, v22
	v_rcp_f32_e32 v23, v23
	v_pk_fma_f32 v[18:19], v[2:3], v[92:93], v[18:19]
	v_pk_mul_f32 v[8:9], v[8:9], v[22:23]
	v_pk_add_f32 v[18:19], v[96:97], v[18:19]
	s_nop 0
	v_pk_mul_f32 v[8:9], v[18:19], v[8:9]
	s_nop 0
	v_cvt_pk_bf16_f32 v5, v8, v9
	v_mov_b64_e32 v[8:9], s[34:35]
	v_mad_i64_i32 v[8:9], s[14:15], v152, s85, v[8:9]
	v_lshl_add_u64 v[8:9], v[186:187], 1, v[8:9]
	global_store_dwordx2 v[8:9], v[4:5], off offset:8
	s_or_b64 exec, exec, s[10:11]
	s_and_saveexec_b64 s[10:11], s[24:25]
	s_cbranch_execz .Lupf_626
.Lupf_632:
	s_waitcnt vmcnt(6)
	v_pk_mul_f32 v[18:19], v[16:17], v[78:79]
	v_pk_fma_f32 v[4:5], v[24:25], v[70:71], v[18:19]
	s_waitcnt vmcnt(5)
	v_pk_fma_f32 v[4:5], v[98:99], v[74:75], v[4:5]
	s_waitcnt vmcnt(4)
	v_pk_add_f32 v[4:5], v[82:83], v[4:5]
	s_waitcnt vmcnt(2)
	v_pk_mul_f32 v[22:23], v[12:13], v[86:87]
	v_pk_mul_f32 v[8:9], v[4:5], v[4:5]
	v_fmamk_f32 v8, v8, 0xbdd2d3e8, v245
	v_fmamk_f32 v9, v9, 0xbdd2d3e8, v245
	v_mul_f32_e32 v8, v4, v8
	v_mul_f32_e32 v9, v5, v9
	v_exp_f32_e32 v8, v8
	v_exp_f32_e32 v9, v9
	v_pk_fma_f32 v[18:19], v[20:21], v[66:67], v[22:23]
	v_add_f32_e32 v8, 1.0, v8
	v_add_f32_e32 v9, 1.0, v9
	v_rcp_f32_e32 v8, v8
	v_rcp_f32_e32 v9, v9
	s_waitcnt vmcnt(1)
	v_pk_fma_f32 v[18:19], v[46:47], v[90:91], v[18:19]
	v_pk_mul_f32 v[20:21], v[6:7], v[80:81]
	s_waitcnt vmcnt(0)
	v_pk_add_f32 v[18:19], v[94:95], v[18:19]
	v_pk_mul_f32 v[4:5], v[4:5], v[8:9]
	v_pk_fma_f32 v[8:9], v[14:15], v[72:73], v[20:21]
	v_pk_fma_f32 v[8:9], v[48:49], v[76:77], v[8:9]
	v_pk_add_f32 v[8:9], v[84:85], v[8:9]
	v_pk_mul_f32 v[20:21], v[2:3], v[88:89]
	v_pk_mul_f32 v[14:15], v[8:9], v[8:9]
	v_pk_mul_f32 v[4:5], v[18:19], v[4:5]
	v_fmamk_f32 v14, v14, 0xbdd2d3e8, v245
	v_fmamk_f32 v15, v15, 0xbdd2d3e8, v245
	v_mul_f32_e32 v14, v8, v14
	v_mul_f32_e32 v15, v9, v15
	v_exp_f32_e32 v14, v14
	v_exp_f32_e32 v15, v15
	v_add_f32_e32 v14, 1.0, v14
	v_add_f32_e32 v15, 1.0, v15
	v_rcp_f32_e32 v14, v14
	v_rcp_f32_e32 v15, v15
	v_pk_fma_f32 v[10:11], v[10:11], v[68:69], v[20:21]
	v_cvt_pk_bf16_f32 v4, v4, v5
	v_pk_fma_f32 v[10:11], v[42:43], v[92:93], v[10:11]
	v_pk_mul_f32 v[8:9], v[8:9], v[14:15]
	v_pk_add_f32 v[10:11], v[96:97], v[10:11]
	s_nop 0
	v_pk_mul_f32 v[8:9], v[10:11], v[8:9]
	s_nop 0
	v_cvt_pk_bf16_f32 v5, v8, v9
	v_mov_b64_e32 v[8:9], s[34:35]
	v_mad_i64_i32 v[8:9], s[12:13], v153, s85, v[8:9]
	v_lshl_add_u64 v[8:9], v[186:187], 1, v[8:9]
	global_store_dwordx2 v[8:9], v[4:5], off offset:8
	s_or_b64 exec, exec, s[10:11]
	s_and_saveexec_b64 s[10:11], s[28:29]
	s_cbranch_execnz .Lupf_627
	s_branch .Lupf_628
